# mem-unit prologue: 12 key-row loads of pieces 2..7 issued up front (counted vmcnt + register copies) instead of 6 serial round trips
# baseline (speedup 1.0000x reference)
; __device__ __forceinline__ int opaque_tid(int wv) { int lane_; asm volatile("v_mbcnt_lo_u32_b32 %0, -1, 0\n\tv_mbcnt_hi_u32_b32 %0, -1, %0" : "=v"(lane_)); return wv * 64 + lane_; }
; __device__ __forceinline__ float wave_max(float v) { v = fmaxf(v, swz_xor<1>(v)); v = fmaxf(v, swz_xor<2>(v)); v = fmaxf(v, swz_xor<4>(v)); v = fmaxf(v, swz_xor<8>(v)); v = fmaxf(v, swz_xor<16>(v)); return xmax32(v); }
; __device__ __forceinline__ void mem_unit(const MemArgs& A, int unit, char* lds, int wv) {
;     const int tid = opaque_tid(wv), wid = __builtin_amdgcn_readfirstlane(tid >> 6), lane = tid & 63, r32 = lane & 31, hi = lane >> 5;
;     const int b = unit / (4 * 32), hm = (unit / 32) % 4, qb = unit % 32;
;     const bf16* Kh = A.mkv + (size_t)b * NMEM * MKVC + A.layer * 1024 + hm * 128;
;     const bf16* Vh = Kh + 512;
;     char* V_lds = lds; char* K_lds = lds + 4 * SHM_V;
;     float* wsl = (float*)(lds + 131072) + wid * 64;
;     float nM2;
;     { const float a = wave_max(fmaxf(fabsf(A.gmq[lane]), fabsf(A.gmq[lane + 64]))), bb = wave_max(fmaxf(fabsf(A.gmk[lane]), fabsf(A.gmk[lane + 64])));
;       nM2 = -(11.3137085f * a * bb * LOG2E * 1.03f + 0.25f); }
;     { const int sr = tid >> 4, sc = (tid & 15) * 8, kc = sc * 2;
;       const f32x4 g0 = *(const f32x4*)(A.gmk + sc), g1 = *(const f32x4*)(A.gmk + sc + 4);
; #pragma unroll
;       for (int t = 0; t < 4; ++t)
; #pragma unroll
;         for (int hh = 0; hh < 2; ++hh) { const int key = t * 64 + hh * 32 + sr;
;           const bf16x8 v8 = *reinterpret_cast<const bf16x8*>(&Vh[(size_t)key * MKVC + sc]); const bf16x8 k8 = *reinterpret_cast<const bf16x8*>(&Kh[(size_t)key * MKVC + sc]);
; __global__ void __launch_bounds__(512) fwd_megakernel(Args args) {
;     ...
;                 if (it >= 768 + 256 + 256) break;
;                 if (it < 768) { const int r = it & 127; att::diff_unit(DA, r >> 6, 5 - (it >> 7), r & 63, (char*)lds, wave); }
;                 else if (it < 1024) { att::conv_items(CA, (long)(it - 768) * 512 + opaque_tid(wave), 256L * 512); __syncthreads(); }
;                 else att::mem_unit(MA, it - 1024, (char*)lds, wave); }
.LBB0_196:
	s_cmpk_gt_i32 s20, 0x4ff
	s_mov_b64 s[6:7], -1
	s_cbranch_scc1 .LBB0_195
	s_cmpk_gt_i32 s20, 0x2ff
	s_cbranch_scc0 .LBB0_213
	s_cmpk_gt_u32 s20, 0x3ff
	s_cbranch_scc0 .LBB0_204
	s_add_i32 s3, s20, 0xfffffc00
	v_mbcnt_lo_u32_b32 v78, -1, 0
	v_mbcnt_hi_u32_b32 v78, -1, v78
	v_readlane_b32 s16, v255, 0
	v_and_b32_e32 v145, 63, v78
	s_lshr_b32 s84, s3, 7
	v_lshlrev_b32_e32 v0, 2, v145
	v_readlane_b32 s17, v255, 1
	s_lshl_b64 s[0:1], s[84:85], 21
	v_readlane_b32 s2, v255, 4
	global_load_dword v6, v0, s[40:41]
	global_load_dword v7, v0, s[40:41] offset:256
	s_nop 0
	global_load_dword v8, v0, s[16:17]
	global_load_dword v9, v0, s[16:17] offset:256
	s_add_u32 s2, s2, s0
	v_readlane_b32 s0, v255, 5
	v_add_u32_e32 v40, s44, v78
	s_addc_u32 s1, s0, s1
	s_lshl_b32 s0, s3, 2
	s_and_b32 s0, s0, 0x180
	v_ashrrev_i32_e32 v28, 4, v40
	v_lshlrev_b32_e32 v16, 3, v78
	s_lshl_b32 s6, s0, 1
	v_and_b32_e32 v17, 0x78, v16
	v_ashrrev_i32_e32 v29, 31, v28
	s_add_u32 s8, s2, s6
	v_lshlrev_b32_e32 v18, 1, v17
	v_lshlrev_b64 v[0:1], 13, v[28:29]
	s_addc_u32 s9, s1, 0
	v_or_b32_e32 v0, v0, v18
	v_lshl_add_u64 v[24:25], s[8:9], 0, v[0:1]
	global_load_dwordx4 v[0:3], v[24:25], off
	v_add_u32_e32 v26, 32, v28
	v_ashrrev_i32_e32 v27, 31, v26
	v_lshlrev_b64 v[4:5], 13, v[26:27]
	v_or_b32_e32 v4, v4, v18
	v_lshl_add_u64 v[4:5], s[8:9], 0, v[4:5]
	v_and_b32_e32 v19, 0xf0, v40
	s_add_i32 s2, 0, 0x10000
	v_xad_u32 v56, v18, v19, s2
	s_mov_b32 s18, 0xf800000
	v_bfe_u32 v57, v16, 5, 2
	v_lshlrev_b32_e32 v16, 6, v28
	v_and_b32_e32 v16, 0x1c0, v16
	v_readfirstlane_b32 s1, v40
	s_lshl_b32 s3, s3, 8
	s_and_b32 s3, s3, 0x1f00
	v_and_b32_e32 v144, 31, v78
	s_mov_b32 s7, s85
	v_bfe_u32 v146, v78, 5, 1
	v_lshlrev_b32_e32 v176, 4, v146
	v_and_b32_e32 v108, 32, v78
	s_mov_b32 s2, 0
	s_waitcnt vmcnt(4)
	v_max_f32_e64 v6, |v6|, |v6|
	s_waitcnt vmcnt(3)
	v_max_f32_e64 v7, |v7|, |v7|
	s_waitcnt vmcnt(1)
	v_max_f32_e64 v9, |v9|, |v9|
	v_max_f32_e64 v8, |v8|, |v8|
	v_max_f32_e32 v6, v6, v7
	v_max_f32_e32 v7, v8, v9
	ds_swizzle_b32 v27, v6 offset:swizzle(SWAP,1)
	ds_swizzle_b32 v29, v7 offset:swizzle(SWAP,1)
	global_load_dwordx4 v[12:15], v[24:25], off offset:1024
	global_load_dwordx4 v[8:11], v[4:5], off offset:1024
	global_load_dwordx4 v[20:23], v[4:5], off
	s_waitcnt lgkmcnt(1)
	v_max_f32_e32 v4, v27, v27
	s_waitcnt lgkmcnt(0)
	v_max_f32_e32 v5, v29, v29
	v_max_f32_e32 v27, v6, v4
	v_max_f32_e32 v29, v7, v5
	ds_swizzle_b32 v38, v27 offset:swizzle(SWAP,2)
	ds_swizzle_b32 v39, v29 offset:swizzle(SWAP,2)
	s_waitcnt vmcnt(3)
	v_and_b32_e32 v37, 0xffff0000, v0
	v_lshlrev_b32_e32 v36, 16, v0
	v_and_b32_e32 v35, 0xffff0000, v1
	v_lshlrev_b32_e32 v34, 16, v1
	v_pk_mul_f32 v[6:7], v[36:37], v[36:37]
	v_pk_mul_f32 v[4:5], v[34:35], v[34:35]
	v_add_f32_e32 v6, v6, v7
	v_and_b32_e32 v33, 0xffff0000, v2
	v_lshlrev_b32_e32 v32, 16, v2
	v_add_f32_e32 v4, v4, v6
	v_and_b32_e32 v31, 0xffff0000, v3
	v_lshlrev_b32_e32 v30, 16, v3
	v_pk_mul_f32 v[2:3], v[32:33], v[32:33]
	v_add_f32_e32 v4, v5, v4
	v_add_f32_e32 v2, v2, v4
	v_pk_mul_f32 v[0:1], v[30:31], v[30:31]
	v_add_f32_e32 v2, v3, v2
	s_waitcnt lgkmcnt(1)
	v_max_f32_e32 v3, v38, v38
	s_waitcnt lgkmcnt(0)
	v_max_f32_e32 v4, v39, v39
	v_add_f32_e32 v0, v0, v2
	v_max_f32_e32 v2, v27, v3
	v_max_f32_e32 v3, v29, v4
	v_add_f32_e32 v0, v1, v0
	ds_swizzle_b32 v1, v2 offset:swizzle(SWAP,4)
	ds_swizzle_b32 v4, v3 offset:swizzle(SWAP,4)
	ds_swizzle_b32 v5, v0 offset:swizzle(SWAP,1)
	v_lshlrev_b32_e32 v6, 2, v17
	v_and_b32_e32 v27, 8, v28
	s_waitcnt lgkmcnt(2)
	v_max_f32_e32 v1, v1, v1
	s_waitcnt lgkmcnt(1)
	v_max_f32_e32 v4, v4, v4
	s_waitcnt lgkmcnt(0)
	v_add_f32_e32 v17, v0, v5
	v_max_f32_e32 v29, v2, v1
	v_max_f32_e32 v38, v3, v4
	global_load_dwordx4 v[0:3], v6, s[16:17] offset:16
	s_nop 0
	global_load_dwordx4 v[4:7], v6, s[16:17]
	s_mov_b32 s100, 0x80000
	s_mov_b32 s101, 0
	v_lshl_add_u64 v[80:81], v[24:25], 0, s[100:101]
	global_load_dwordx4 v[62:65], v[80:81], off offset:1024
	global_load_dwordx4 v[66:69], v[80:81], off
	s_mov_b32 s100, 0xc0000
	s_mov_b32 s101, 0
	v_lshl_add_u64 v[80:81], v[24:25], 0, s[100:101]
	global_load_dwordx4 v[70:73], v[80:81], off offset:1024
	global_load_dwordx4 v[74:77], v[80:81], off
	s_mov_b32 s100, 0x100000
	s_mov_b32 s101, 0
	v_lshl_add_u64 v[80:81], v[24:25], 0, s[100:101]
	global_load_dwordx4 v[112:115], v[80:81], off offset:1024
	global_load_dwordx4 v[116:119], v[80:81], off
	s_mov_b32 s100, 0x140000
	s_mov_b32 s101, 0
	v_lshl_add_u64 v[80:81], v[24:25], 0, s[100:101]
	global_load_dwordx4 v[120:123], v[80:81], off offset:1024
	global_load_dwordx4 v[124:127], v[80:81], off
	s_mov_b32 s100, 0x180000
	s_mov_b32 s101, 0
	v_lshl_add_u64 v[80:81], v[24:25], 0, s[100:101]
	global_load_dwordx4 v[128:131], v[80:81], off offset:1024
	global_load_dwordx4 v[132:135], v[80:81], off
	s_mov_b32 s100, 0x1c0000
	s_mov_b32 s101, 0
	v_lshl_add_u64 v[80:81], v[24:25], 0, s[100:101]
	global_load_dwordx4 v[136:139], v[80:81], off offset:1024
	global_load_dwordx4 v[140:143], v[80:81], off
	ds_swizzle_b32 v39, v17 offset:swizzle(SWAP,2)
	ds_swizzle_b32 v41, v29 offset:swizzle(SWAP,8)
	ds_swizzle_b32 v42, v38 offset:swizzle(SWAP,8)
	s_waitcnt lgkmcnt(2)
	v_add_f32_e32 v17, v17, v39
	s_waitcnt lgkmcnt(1)
	v_max_f32_e32 v39, v41, v41
	s_waitcnt lgkmcnt(0)
	v_max_f32_e32 v41, v42, v42
	ds_swizzle_b32 v42, v17 offset:swizzle(SWAP,4)
	v_max_f32_e32 v29, v29, v39
	v_max_f32_e32 v38, v38, v41
	ds_swizzle_b32 v39, v29 offset:swizzle(SWAP,16)
	ds_swizzle_b32 v41, v38 offset:swizzle(SWAP,16)
	s_waitcnt lgkmcnt(2)
	v_add_f32_e32 v17, v17, v42
	ds_swizzle_b32 v19, v17 offset:swizzle(SWAP,8)
	s_waitcnt lgkmcnt(2)
	v_max_f32_e32 v39, v39, v39
	s_waitcnt lgkmcnt(1)
; template <int X> __device__ __forceinline__ float swz_xor(float v) { return __int_as_float(__builtin_amdgcn_ds_swizzle(__float_as_int(v), (X << 10) | 0x1f)); }
; __device__ __forceinline__ unsigned cvtpk(float lo, float hi) { f32x2_t v = {lo, hi}; bf16x2_t b = __builtin_convertvector(v, bf16x2_t); return __builtin_bit_cast(unsigned, b); }
; __device__ __forceinline__ float bf2f(unsigned short h) { return __uint_as_float(((unsigned)h) << 16); }
; __device__ __forceinline__ float wave_max(float v) { v = fmaxf(v, swz_xor<1>(v)); v = fmaxf(v, swz_xor<2>(v)); v = fmaxf(v, swz_xor<4>(v)); v = fmaxf(v, swz_xor<8>(v)); v = fmaxf(v, swz_xor<16>(v)); return xmax32(v); }
; __device__ __forceinline__ void mem_unit(const MemArgs& A, int unit, char* lds, int wv) {
;     ...
;     float nM2;
;     { const float a = wave_max(fmaxf(fabsf(A.gmq[lane]), fabsf(A.gmq[lane + 64]))), bb = wave_max(fmaxf(fabsf(A.gmk[lane]), fabsf(A.gmk[lane + 64])));
;       nM2 = -(11.3137085f * a * bb * LOG2E * 1.03f + 0.25f); }
;     { const int sr = tid >> 4, sc = (tid & 15) * 8, kc = sc * 2;
;       const f32x4 g0 = *(const f32x4*)(A.gmk + sc), g1 = *(const f32x4*)(A.gmk + sc + 4);
; #pragma unroll
;       for (int t = 0; t < 4; ++t)
; #pragma unroll
;         for (int hh = 0; hh < 2; ++hh) { const int key = t * 64 + hh * 32 + sr;
;           const bf16x8 v8 = *reinterpret_cast<const bf16x8*>(&Vh[(size_t)key * MKVC + sc]); const bf16x8 k8 = *reinterpret_cast<const bf16x8*>(&Kh[(size_t)key * MKVC + sc]);
;           float f[8]; float ss = 0.f;
; #pragma unroll
;           for (int i = 0; i < 8; ++i) { f[i] = bf2f((unsigned short)k8[i]); ss += f[i] * f[i]; }
;           ss += swz_xor<1>(ss); ss += swz_xor<2>(ss); ss += swz_xor<4>(ss); ss += swz_xor<8>(ss);
;           const float rn = 1.0f / sqrtf(ss * (1.0f / 128.0f) + EPS);
;           u32x4 w; w.x = cvtpk(f[0] * rn * g0.x, f[1] * rn * g0.y); w.y = cvtpk(f[2] * rn * g0.z, f[3] * rn * g0.w); w.z = cvtpk(f[4] * rn * g1.x, f[5] * rn * g1.y); w.w = cvtpk(f[6] * rn * g1.z, f[7] * rn * g1.w);
;           *(u32x4*)(K_lds + t * SHM_K + KSWZ(hh * 32 + sr, kc)) = w;
;           { const int ks_ = hh * 32 + sr, kp_ = (ks_ & ~0xC) | ((ks_ & 4) << 1) | ((ks_ & 8) >> 1);
;             *(bf16x8*)(V_lds + t * SHM_V + v_st(kp_, sc)) = v8; } } }
	v_max_f32_e32 v41, v41, v41
	v_max_f32_e32 v29, v29, v39
	v_max_f32_e32 v38, v38, v41
	v_mov_b32_e32 v39, v29
	v_mov_b32_e32 v41, v38
	s_nop 0
	v_permlane32_swap_b32_e32 v29, v39
	v_permlane32_swap_b32_e32 v38, v41
	v_max_f32_e32 v39, v39, v39
	v_max_f32_e32 v29, v29, v29
	v_max_f32_e32 v41, v41, v41
	v_max_f32_e32 v38, v38, v38
	s_waitcnt lgkmcnt(0)
	v_add_f32_e32 v17, v17, v19
	v_max_f32_e32 v19, v29, v39
	v_max_f32_e32 v29, v38, v41
	v_fmamk_f32 v17, v17, 0x3c000000, v224
	v_mul_f32_e32 v19, 0x413504f3, v19
	v_mul_f32_e32 v38, 0x4f800000, v17
	v_mul_f32_e32 v19, v19, v29
	v_cmp_gt_f32_e32 vcc, s18, v17
	v_mul_f32_e32 v19, 0x3fb8aa3b, v19
	v_mov_b32_e32 v29, 0x3e800000
	v_cndmask_b32_e32 v17, v17, v38, vcc
	v_fmamk_f32 v79, v19, 0x3f83d70a, v29
	v_sqrt_f32_e32 v19, v17
	s_waitcnt vmcnt(14)
	v_and_b32_e32 v51, 0xffff0000, v21
	v_lshlrev_b32_e32 v50, 16, v21
	v_and_b32_e32 v21, 0xffff0000, v20
	v_add_u32_e32 v29, -1, v19
	v_fma_f32 v38, -v29, v19, v17
	v_cmp_ge_f32_e64 s[36:37], 0, v38
	v_add_u32_e32 v38, 1, v19
	v_lshlrev_b32_e32 v20, 16, v20
	v_cndmask_b32_e64 v29, v19, v29, s[36:37]
	v_fma_f32 v19, -v38, v19, v17
	v_cmp_lt_f32_e64 s[36:37], 0, v19
	v_pk_mul_f32 v[54:55], v[20:21], v[20:21]
	v_pk_mul_f32 v[52:53], v[50:51], v[50:51]
	v_cndmask_b32_e64 v19, v29, v38, s[36:37]
	v_mul_f32_e32 v29, 0x37800000, v19
	v_cndmask_b32_e32 v19, v19, v29, vcc
	v_cmp_class_f32_e32 vcc, v17, v250
	v_add_f32_e32 v54, v54, v55
	v_and_b32_e32 v39, 0xffff0000, v23
	v_cndmask_b32_e32 v29, v19, v17, vcc
	v_div_scale_f32 v41, s[8:9], v29, v29, 1.0
	v_rcp_f32_e32 v58, v41
	v_and_b32_e32 v17, 48, v18
	v_add3_u32 v59, 0, v16, v17
	v_div_scale_f32 v60, vcc, 1.0, v29, 1.0
	v_fma_f32 v16, -v41, v58, 1.0
	v_fmac_f32_e32 v58, v16, v58
	v_lshlrev_b32_e32 v38, 16, v23
	v_and_b32_e32 v23, 0xffff0000, v22
	v_lshlrev_b32_e32 v22, 16, v22
	v_add_f32_e32 v52, v52, v54
	v_mul_f32_e32 v61, v60, v58
	v_pk_mul_f32 v[48:49], v[22:23], v[22:23]
	v_add_f32_e32 v52, v53, v52
	v_fma_f32 v16, -v41, v61, v60
	s_mov_b64 s[8:9], 0x80000
	v_add_f32_e32 v48, v48, v52
	v_fmac_f32_e32 v61, v16, v58
	v_pk_mul_f32 v[46:47], v[38:39], v[38:39]
	v_lshl_add_u64 v[16:17], v[24:25], 0, s[8:9]
	s_mov_b32 s8, 0x80000
	v_add_f32_e32 v48, v49, v48
	v_add_co_u32_e64 v42, s[36:37], s8, v24
	v_add_f32_e32 v46, v46, v48
	s_nop 0
	v_addc_co_u32_e64 v43, s[36:37], 0, v25, s[36:37]
	v_add_f32_e32 v46, v47, v46
	s_waitcnt vmcnt(10)
	v_mov_b32_e32 v16, v62
	v_mov_b32_e32 v17, v63
	v_mov_b32_e32 v18, v64
	v_mov_b32_e32 v19, v65
	s_nop 0
	v_mov_b32_e32 v42, v66
	v_mov_b32_e32 v43, v67
	v_mov_b32_e32 v44, v68
	v_mov_b32_e32 v45, v69
	ds_swizzle_b32 v47, v46 offset:swizzle(SWAP,1)
	v_fma_f32 v41, -v41, v61, v60
	v_div_fmas_f32 v41, v41, v58, v61
	v_div_fixup_f32 v52, v41, v29, 1.0
	v_pk_mul_f32 v[36:37], v[52:53], v[36:37] op_sel_hi:[0,1]
	s_waitcnt lgkmcnt(0)
	v_add_f32_e32 v29, v46, v47
	ds_swizzle_b32 v41, v29 offset:swizzle(SWAP,2)
	s_nop 0
	v_pk_mul_f32 v[36:37], v[4:5], v[36:37]
	v_pk_mul_f32 v[34:35], v[52:53], v[34:35] op_sel_hi:[0,1]
	v_cvt_pk_bf16_f32 v46, v36, v37
	v_pk_mul_f32 v[34:35], v[6:7], v[34:35]
	s_waitcnt lgkmcnt(0)
	v_add_f32_e32 v29, v29, v41
	ds_swizzle_b32 v36, v29 offset:swizzle(SWAP,4)
	v_cvt_pk_bf16_f32 v47, v34, v35
	v_pk_mul_f32 v[30:31], v[52:53], v[30:31] op_sel_hi:[0,1]
	v_pk_mul_f32 v[30:31], v[2:3], v[30:31]
	v_pk_mul_f32 v[32:33], v[52:53], v[32:33] op_sel_hi:[0,1]
	s_waitcnt lgkmcnt(0)
	v_add_f32_e32 v29, v29, v36
	ds_swizzle_b32 v34, v29 offset:swizzle(SWAP,8)
	v_cvt_pk_bf16_f32 v49, v30, v31
	v_pk_mul_f32 v[32:33], v[0:1], v[32:33]
	s_waitcnt lgkmcnt(0)
	v_add_f32_e32 v29, v29, v34
	v_fmamk_f32 v29, v29, 0x3c000000, v224
	v_mul_f32_e32 v30, 0x4f800000, v29
	v_cmp_gt_f32_e32 vcc, s18, v29
	v_cvt_pk_bf16_f32 v48, v32, v33
	s_nop 0
	v_cndmask_b32_e32 v29, v29, v30, vcc
	v_sqrt_f32_e32 v31, v29
	v_lshl_add_u32 v30, v28, 8, v56
	v_lshrrev_b32_e32 v28, 5, v40
	ds_write_b128 v30, v[46:49]
	v_add_u32_e32 v32, -1, v31
	v_fma_f32 v33, -v32, v31, v29
	v_cmp_ge_f32_e64 s[36:37], 0, v33
	v_add_u32_e32 v33, 1, v31
	s_nop 0
	v_and_b32_e32 v47, 0xffff0000, v43
	v_cndmask_b32_e64 v32, v31, v32, s[36:37]
	v_fma_f32 v31, -v33, v31, v29
	v_cmp_lt_f32_e64 s[36:37], 0, v31
	v_lshlrev_b32_e32 v46, 16, v43
	v_and_b32_e32 v43, 0xffff0000, v42
	v_cndmask_b32_e64 v31, v32, v33, s[36:37]
	v_mul_f32_e32 v32, 0x37800000, v31
	v_cndmask_b32_e32 v31, v31, v32, vcc
	v_cmp_class_f32_e32 vcc, v29, v250
	v_lshlrev_b32_e32 v42, 16, v42
	v_pk_mul_f32 v[52:53], v[42:43], v[42:43]
	v_cndmask_b32_e32 v54, v31, v29, vcc
	v_div_scale_f32 v32, s[8:9], v54, v54, 1.0
	v_rcp_f32_e32 v55, v32
	s_mov_b32 s8, 0x7ffffc
	v_and_or_b32 v28, v28, s8, v57
	v_lshl_add_u32 v31, v28, 9, v59
	ds_write_b128 v31, v[12:15]
	v_fma_f32 v12, -v32, v55, 1.0
	v_fmac_f32_e32 v55, v12, v55
	v_div_scale_f32 v33, vcc, 1.0, v54, 1.0
	v_mul_f32_e32 v58, v33, v55
	v_fma_f32 v12, -v32, v58, v33
	s_mov_b64 s[8:9], 0xc0000
	v_fmac_f32_e32 v58, v12, v55
	v_lshl_add_u64 v[12:13], v[24:25], 0, s[8:9]
	s_mov_b32 s8, 0xc0000
	v_add_co_u32_e64 v28, s[36:37], s8, v24
	v_pk_mul_f32 v[48:49], v[46:47], v[46:47]
	s_nop 0
	v_addc_co_u32_e64 v29, s[36:37], 0, v25, s[36:37]
	s_waitcnt vmcnt(8)
	v_mov_b32_e32 v12, v70
	v_mov_b32_e32 v13, v71
	v_mov_b32_e32 v14, v72
	v_mov_b32_e32 v15, v73
	s_nop 0
	v_mov_b32_e32 v34, v74
	v_mov_b32_e32 v35, v75
	v_mov_b32_e32 v36, v76
	v_mov_b32_e32 v37, v77
	v_add_f32_e32 v52, v52, v53
	v_and_b32_e32 v29, 0xffff0000, v45
	v_lshlrev_b32_e32 v28, 16, v45
	v_and_b32_e32 v45, 0xffff0000, v44
	v_lshlrev_b32_e32 v44, 16, v44
	v_add_f32_e32 v48, v48, v52
	v_pk_mul_f32 v[40:41], v[44:45], v[44:45]
	v_add_f32_e32 v48, v49, v48
	v_add_f32_e32 v40, v40, v48
	v_fma_f32 v60, -v32, v58, v33
	v_pk_mul_f32 v[32:33], v[28:29], v[28:29]
	v_add_f32_e32 v40, v41, v40
	v_add_f32_e32 v32, v32, v40
	v_add_f32_e32 v33, v33, v32
	ds_swizzle_b32 v40, v33 offset:swizzle(SWAP,1)
	v_div_fmas_f32 v32, v60, v55, v58
	v_div_fixup_f32 v32, v32, v54, 1.0
	v_pk_mul_f32 v[20:21], v[32:33], v[20:21] op_sel_hi:[0,1]
	v_pk_mul_f32 v[20:21], v[4:5], v[20:21]
	s_waitcnt lgkmcnt(0)
; template <int X> __device__ __forceinline__ float swz_xor(float v) { return __int_as_float(__builtin_amdgcn_ds_swizzle(__float_as_int(v), (X << 10) | 0x1f)); }
; __device__ __forceinline__ unsigned cvtpk(float lo, float hi) { f32x2_t v = {lo, hi}; bf16x2_t b = __builtin_convertvector(v, bf16x2_t); return __builtin_bit_cast(unsigned, b); }
; __device__ __forceinline__ float bf2f(unsigned short h) { return __uint_as_float(((unsigned)h) << 16); }
; __device__ __forceinline__ int v_st(int k, int c) { const int kk = (k & ~0xC) | ((k & 4) << 1) | ((k & 8) >> 1); return ((kk >> 3) * 4 + (c >> 5)) * 512 + ((kk & 7) * 32 + (c & 31)) * 2; }
; __device__ __forceinline__ void mem_unit(const MemArgs& A, int unit, char* lds, int wv) {
;     ...
;     { const int sr = tid >> 4, sc = (tid & 15) * 8, kc = sc * 2;
;       const f32x4 g0 = *(const f32x4*)(A.gmk + sc), g1 = *(const f32x4*)(A.gmk + sc + 4);
; #pragma unroll
;       for (int t = 0; t < 4; ++t)
; #pragma unroll
;         for (int hh = 0; hh < 2; ++hh) { const int key = t * 64 + hh * 32 + sr;
;           const bf16x8 v8 = *reinterpret_cast<const bf16x8*>(&Vh[(size_t)key * MKVC + sc]); const bf16x8 k8 = *reinterpret_cast<const bf16x8*>(&Kh[(size_t)key * MKVC + sc]);
;           float f[8]; float ss = 0.f;
; #pragma unroll
;           for (int i = 0; i < 8; ++i) { f[i] = bf2f((unsigned short)k8[i]); ss += f[i] * f[i]; }
;           ss += swz_xor<1>(ss); ss += swz_xor<2>(ss); ss += swz_xor<4>(ss); ss += swz_xor<8>(ss);
;           const float rn = 1.0f / sqrtf(ss * (1.0f / 128.0f) + EPS);
;           u32x4 w; w.x = cvtpk(f[0] * rn * g0.x, f[1] * rn * g0.y); w.y = cvtpk(f[2] * rn * g0.z, f[3] * rn * g0.w); w.z = cvtpk(f[4] * rn * g1.x, f[5] * rn * g1.y); w.w = cvtpk(f[6] * rn * g1.z, f[7] * rn * g1.w);
;           *(u32x4*)(K_lds + t * SHM_K + KSWZ(hh * 32 + sr, kc)) = w;
;           { const int ks_ = hh * 32 + sr, kp_ = (ks_ & ~0xC) | ((ks_ & 4) << 1) | ((ks_ & 8) >> 1);
;             *(bf16x8*)(V_lds + t * SHM_V + v_st(kp_, sc)) = v8; } } }
	v_add_f32_e32 v33, v33, v40
	ds_swizzle_b32 v48, v33 offset:swizzle(SWAP,2)
	v_pk_mul_f32 v[40:41], v[32:33], v[50:51] op_sel_hi:[0,1]
	v_pk_mul_f32 v[40:41], v[6:7], v[40:41]
	v_cvt_pk_bf16_f32 v20, v20, v21
	v_cvt_pk_bf16_f32 v21, v40, v41
	s_waitcnt lgkmcnt(0)
	v_add_f32_e32 v33, v33, v48
	ds_swizzle_b32 v48, v33 offset:swizzle(SWAP,4)
	v_pk_mul_f32 v[22:23], v[32:33], v[22:23] op_sel_hi:[0,1]
	v_pk_mul_f32 v[22:23], v[0:1], v[22:23]
	s_mov_b32 s8, 0xfffff0
	v_cvt_pk_bf16_f32 v22, v22, v23
	s_waitcnt lgkmcnt(0)
	v_add_f32_e32 v40, v33, v48
	ds_swizzle_b32 v41, v40 offset:swizzle(SWAP,8)
	v_pk_mul_f32 v[32:33], v[32:33], v[38:39] op_sel_hi:[0,1]
	v_pk_mul_f32 v[32:33], v[2:3], v[32:33]
	s_nop 0
	v_and_b32_e32 v55, 0xffff0000, v34
	v_cvt_pk_bf16_f32 v23, v32, v33
	s_waitcnt lgkmcnt(0)
	v_add_f32_e32 v33, v40, v41
	v_fmamk_f32 v33, v33, 0x3c000000, v224
	v_mul_f32_e32 v38, 0x4f800000, v33
	v_cmp_gt_f32_e32 vcc, s18, v33
	v_lshl_add_u32 v32, v26, 8, v56
	ds_write_b128 v32, v[20:23]
	v_cndmask_b32_e32 v33, v33, v38, vcc
	v_sqrt_f32_e32 v38, v33
	v_and_or_b32 v20, v26, s8, v27
	v_lshrrev_b32_e32 v48, 1, v20
	s_mov_b64 s[8:9], 0x100000
	v_add_u32_e32 v20, -1, v38
	v_fma_f32 v21, -v20, v38, v33
	v_cmp_ge_f32_e64 s[36:37], 0, v21
	v_add_u32_e32 v21, 1, v38
	v_fma_f32 v22, -v21, v38, v33
	v_cndmask_b32_e64 v20, v38, v20, s[36:37]
	v_cmp_lt_f32_e64 s[36:37], 0, v22
	v_lshlrev_b32_e32 v54, 16, v34
	v_and_b32_e32 v53, 0xffff0000, v35
	v_cndmask_b32_e64 v20, v20, v21, s[36:37]
	v_mul_f32_e32 v21, 0x37800000, v20
	v_cndmask_b32_e32 v20, v20, v21, vcc
	v_cmp_class_f32_e32 vcc, v33, v250
	v_lshlrev_b32_e32 v52, 16, v35
	v_pk_mul_f32 v[34:35], v[54:55], v[54:55]
	v_cndmask_b32_e32 v56, v20, v33, vcc
	v_lshl_add_u64 v[20:21], v[24:25], 0, s[8:9]
	s_mov_b32 s8, 0x100000
	v_add_co_u32_e32 v26, vcc, s8, v24
	v_div_scale_f32 v58, s[8:9], v56, v56, 1.0
	s_nop 0
	v_addc_co_u32_e32 v27, vcc, 0, v25, vcc
	s_waitcnt vmcnt(6)
	v_mov_b32_e32 v20, v112
	v_mov_b32_e32 v21, v113
	v_mov_b32_e32 v22, v114
	v_mov_b32_e32 v23, v115
	s_nop 0
	v_mov_b32_e32 v38, v116
	v_mov_b32_e32 v39, v117
	v_mov_b32_e32 v40, v118
	v_mov_b32_e32 v41, v119
	v_rcp_f32_e32 v60, v58
	v_or_b32_e32 v26, v48, v57
	v_lshl_add_u32 v33, v26, 9, v59
	v_pk_mul_f32 v[26:27], v[52:53], v[52:53]
	v_add_f32_e32 v34, v34, v35
	v_and_b32_e32 v51, 0xffff0000, v36
	v_lshlrev_b32_e32 v50, 16, v36
	v_add_f32_e32 v26, v26, v34
	ds_write_b128 v33, v[8:11]
	v_pk_mul_f32 v[10:11], v[50:51], v[50:51]
	v_add_f32_e32 v26, v27, v26
	v_fma_f32 v8, -v58, v60, 1.0
	v_and_b32_e32 v49, 0xffff0000, v37
	v_lshlrev_b32_e32 v48, 16, v37
	v_add_f32_e32 v10, v10, v26
	v_fmac_f32_e32 v60, v8, v60
	v_pk_mul_f32 v[8:9], v[48:49], v[48:49]
	v_add_f32_e32 v10, v11, v10
	v_add_f32_e32 v8, v8, v10
	v_add_f32_e32 v8, v9, v8
	ds_swizzle_b32 v9, v8 offset:swizzle(SWAP,1)
	v_div_scale_f32 v10, vcc, 1.0, v56, 1.0
	v_mul_f32_e32 v11, v10, v60
	v_fma_f32 v26, -v58, v11, v10
	s_waitcnt lgkmcnt(0)
	v_add_f32_e32 v8, v8, v9
	ds_swizzle_b32 v9, v8 offset:swizzle(SWAP,2)
	v_fmac_f32_e32 v11, v26, v60
	v_fma_f32 v10, -v58, v11, v10
	v_div_fmas_f32 v10, v10, v60, v11
	v_div_fixup_f32 v26, v10, v56, 1.0
	s_waitcnt lgkmcnt(0)
	v_add_f32_e32 v27, v8, v9
	ds_swizzle_b32 v34, v27 offset:swizzle(SWAP,4)
	v_pk_mul_f32 v[8:9], v[26:27], v[42:43] op_sel_hi:[0,1]
	v_pk_mul_f32 v[10:11], v[26:27], v[46:47] op_sel_hi:[0,1]
	v_pk_mul_f32 v[8:9], v[4:5], v[8:9]
	v_pk_mul_f32 v[10:11], v[6:7], v[10:11]
	s_waitcnt lgkmcnt(0)
	v_add_f32_e32 v27, v27, v34
	ds_swizzle_b32 v34, v27 offset:swizzle(SWAP,8)
	v_cvt_pk_bf16_f32 v8, v8, v9
	v_cvt_pk_bf16_f32 v9, v10, v11
	v_pk_mul_f32 v[10:11], v[26:27], v[44:45] op_sel_hi:[0,1]
	v_pk_mul_f32 v[10:11], v[0:1], v[10:11]
	s_waitcnt lgkmcnt(0)
	v_add_f32_e32 v27, v27, v34
	v_fmamk_f32 v27, v27, 0x3c000000, v224
	v_mul_f32_e32 v34, 0x4f800000, v27
	v_cmp_gt_f32_e32 vcc, s18, v27
	v_cvt_pk_bf16_f32 v10, v10, v11
	s_nop 0
	v_and_b32_e32 v45, 0xffff0000, v38
	v_cndmask_b32_e32 v34, v27, v34, vcc
	v_sqrt_f32_e32 v35, v34
	v_pk_mul_f32 v[26:27], v[26:27], v[28:29] op_sel_hi:[0,1]
	v_pk_mul_f32 v[26:27], v[2:3], v[26:27]
	v_lshlrev_b32_e32 v44, 16, v38
	v_add_u32_e32 v11, -1, v35
	v_fma_f32 v28, -v11, v35, v34
	v_cmp_ge_f32_e64 s[36:37], 0, v28
	v_add_u32_e32 v28, 1, v35
	v_fma_f32 v29, -v28, v35, v34
	v_cndmask_b32_e64 v11, v35, v11, s[36:37]
	v_cmp_lt_f32_e64 s[36:37], 0, v29
	v_and_b32_e32 v43, 0xffff0000, v39
	v_lshlrev_b32_e32 v42, 16, v39
	v_cndmask_b32_e64 v11, v11, v28, s[36:37]
	v_mul_f32_e32 v28, 0x37800000, v11
	v_cndmask_b32_e32 v11, v11, v28, vcc
	v_cmp_class_f32_e32 vcc, v34, v250
	v_pk_mul_f32 v[38:39], v[44:45], v[44:45]
	v_and_b32_e32 v29, 0xffff0000, v40
	v_cndmask_b32_e32 v46, v11, v34, vcc
	v_div_scale_f32 v47, s[8:9], v46, v46, 1.0
	v_cvt_pk_bf16_f32 v11, v26, v27
	s_mov_b64 s[8:9], 0x140000
	ds_write_b128 v30, v[8:11] offset:16384
	ds_write_b128 v31, v[16:19] offset:16384
	v_lshl_add_u64 v[10:11], v[24:25], 0, s[8:9]
	s_mov_b32 s8, 0x140000
	v_add_co_u32_e32 v34, vcc, s8, v24
	v_rcp_f32_e32 v56, v47
	s_nop 0
	v_addc_co_u32_e32 v35, vcc, 0, v25, vcc
	s_waitcnt vmcnt(4)
	v_mov_b32_e32 v16, v120
	v_mov_b32_e32 v17, v121
	v_mov_b32_e32 v18, v122
	v_mov_b32_e32 v19, v123
	s_nop 0
	v_mov_b32_e32 v34, v124
	v_mov_b32_e32 v35, v125
	v_mov_b32_e32 v36, v126
	v_mov_b32_e32 v37, v127
	v_and_b32_e32 v27, 0xffff0000, v41
	v_lshlrev_b32_e32 v26, 16, v41
	v_lshlrev_b32_e32 v28, 16, v40
	v_pk_mul_f32 v[40:41], v[42:43], v[42:43]
	v_add_f32_e32 v38, v38, v39
	v_add_f32_e32 v38, v40, v38
	v_pk_mul_f32 v[10:11], v[28:29], v[28:29]
	v_add_f32_e32 v38, v41, v38
	v_fma_f32 v8, -v47, v56, 1.0
	v_add_f32_e32 v10, v10, v38
	v_fmac_f32_e32 v56, v8, v56
	v_pk_mul_f32 v[8:9], v[26:27], v[26:27]
	v_add_f32_e32 v10, v11, v10
	v_add_f32_e32 v8, v8, v10
	v_add_f32_e32 v8, v9, v8
	ds_swizzle_b32 v9, v8 offset:swizzle(SWAP,1)
	v_div_scale_f32 v10, vcc, 1.0, v46, 1.0
	v_mul_f32_e32 v11, v10, v56
	v_fma_f32 v38, -v47, v11, v10
	s_waitcnt lgkmcnt(0)
; template <int X> __device__ __forceinline__ float swz_xor(float v) { return __int_as_float(__builtin_amdgcn_ds_swizzle(__float_as_int(v), (X << 10) | 0x1f)); }
; __device__ __forceinline__ unsigned cvtpk(float lo, float hi) { f32x2_t v = {lo, hi}; bf16x2_t b = __builtin_convertvector(v, bf16x2_t); return __builtin_bit_cast(unsigned, b); }
; __device__ __forceinline__ float bf2f(unsigned short h) { return __uint_as_float(((unsigned)h) << 16); }
; __device__ __forceinline__ int v_st(int k, int c) { const int kk = (k & ~0xC) | ((k & 4) << 1) | ((k & 8) >> 1); return ((kk >> 3) * 4 + (c >> 5)) * 512 + ((kk & 7) * 32 + (c & 31)) * 2; }
; __device__ __forceinline__ void mem_unit(const MemArgs& A, int unit, char* lds, int wv) {
;     ...
;     { const int sr = tid >> 4, sc = (tid & 15) * 8, kc = sc * 2;
;       const f32x4 g0 = *(const f32x4*)(A.gmk + sc), g1 = *(const f32x4*)(A.gmk + sc + 4);
; #pragma unroll
;       for (int t = 0; t < 4; ++t)
; #pragma unroll
;         for (int hh = 0; hh < 2; ++hh) { const int key = t * 64 + hh * 32 + sr;
;           const bf16x8 v8 = *reinterpret_cast<const bf16x8*>(&Vh[(size_t)key * MKVC + sc]); const bf16x8 k8 = *reinterpret_cast<const bf16x8*>(&Kh[(size_t)key * MKVC + sc]);
;           float f[8]; float ss = 0.f;
; #pragma unroll
;           for (int i = 0; i < 8; ++i) { f[i] = bf2f((unsigned short)k8[i]); ss += f[i] * f[i]; }
;           ss += swz_xor<1>(ss); ss += swz_xor<2>(ss); ss += swz_xor<4>(ss); ss += swz_xor<8>(ss);
;           const float rn = 1.0f / sqrtf(ss * (1.0f / 128.0f) + EPS);
;           u32x4 w; w.x = cvtpk(f[0] * rn * g0.x, f[1] * rn * g0.y); w.y = cvtpk(f[2] * rn * g0.z, f[3] * rn * g0.w); w.z = cvtpk(f[4] * rn * g1.x, f[5] * rn * g1.y); w.w = cvtpk(f[6] * rn * g1.z, f[7] * rn * g1.w);
;           *(u32x4*)(K_lds + t * SHM_K + KSWZ(hh * 32 + sr, kc)) = w;
;           { const int ks_ = hh * 32 + sr, kp_ = (ks_ & ~0xC) | ((ks_ & 4) << 1) | ((ks_ & 8) >> 1);
;             *(bf16x8*)(V_lds + t * SHM_V + v_st(kp_, sc)) = v8; } } }
	v_add_f32_e32 v8, v8, v9
	ds_swizzle_b32 v9, v8 offset:swizzle(SWAP,2)
	v_fmac_f32_e32 v11, v38, v56
	v_fma_f32 v10, -v47, v11, v10
	v_div_fmas_f32 v10, v10, v56, v11
	v_div_fixup_f32 v38, v10, v46, 1.0
	s_waitcnt lgkmcnt(0)
	v_add_f32_e32 v39, v8, v9
	ds_swizzle_b32 v40, v39 offset:swizzle(SWAP,4)
	v_pk_mul_f32 v[8:9], v[38:39], v[54:55] op_sel_hi:[0,1]
	v_pk_mul_f32 v[10:11], v[38:39], v[52:53] op_sel_hi:[0,1]
	v_pk_mul_f32 v[8:9], v[4:5], v[8:9]
	v_pk_mul_f32 v[10:11], v[6:7], v[10:11]
	s_waitcnt lgkmcnt(0)
	v_add_f32_e32 v39, v39, v40
	ds_swizzle_b32 v40, v39 offset:swizzle(SWAP,8)
	v_cvt_pk_bf16_f32 v8, v8, v9
	v_cvt_pk_bf16_f32 v9, v10, v11
	v_pk_mul_f32 v[10:11], v[38:39], v[50:51] op_sel_hi:[0,1]
	v_pk_mul_f32 v[10:11], v[0:1], v[10:11]
	s_waitcnt lgkmcnt(0)
	v_add_f32_e32 v39, v39, v40
	v_fmamk_f32 v39, v39, 0x3c000000, v224
	v_mul_f32_e32 v40, 0x4f800000, v39
	v_cmp_gt_f32_e32 vcc, s18, v39
	v_cvt_pk_bf16_f32 v10, v10, v11
	s_nop 0
	v_and_b32_e32 v47, 0xffff0000, v37
	v_cndmask_b32_e32 v40, v39, v40, vcc
	v_sqrt_f32_e32 v41, v40
	v_pk_mul_f32 v[38:39], v[38:39], v[48:49] op_sel_hi:[0,1]
	v_pk_mul_f32 v[38:39], v[2:3], v[38:39]
	v_and_b32_e32 v49, 0xffff0000, v35
	v_add_u32_e32 v11, -1, v41
	v_fma_f32 v46, -v11, v41, v40
	v_cmp_ge_f32_e64 s[36:37], 0, v46
	v_add_u32_e32 v46, 1, v41
	v_lshlrev_b32_e32 v48, 16, v35
	v_cndmask_b32_e64 v11, v41, v11, s[36:37]
	v_fma_f32 v41, -v46, v41, v40
	v_cmp_lt_f32_e64 s[36:37], 0, v41
	v_and_b32_e32 v35, 0xffff0000, v34
	v_lshlrev_b32_e32 v34, 16, v34
	v_cndmask_b32_e64 v11, v11, v46, s[36:37]
	v_mul_f32_e32 v41, 0x37800000, v11
	v_cndmask_b32_e32 v11, v11, v41, vcc
	v_cmp_class_f32_e32 vcc, v40, v250
	v_pk_mul_f32 v[52:53], v[34:35], v[34:35]
	v_pk_mul_f32 v[50:51], v[48:49], v[48:49]
	v_cndmask_b32_e32 v54, v11, v40, vcc
	v_div_scale_f32 v55, s[8:9], v54, v54, 1.0
	v_rcp_f32_e32 v56, v55
	v_cvt_pk_bf16_f32 v11, v38, v39
	ds_write_b128 v32, v[8:11] offset:16384
	ds_write_b128 v33, v[12:15] offset:16384
	s_mov_b64 s[8:9], 0x180000
	v_fma_f32 v8, -v55, v56, 1.0
	v_fmac_f32_e32 v56, v8, v56
	v_lshl_add_u64 v[8:9], v[24:25], 0, s[8:9]
	s_mov_b32 s8, 0x180000
	v_add_co_u32_e32 v12, vcc, s8, v24
	v_add_f32_e32 v52, v52, v53
	s_nop 0
	v_addc_co_u32_e32 v13, vcc, 0, v25, vcc
	s_waitcnt vmcnt(2)
	v_mov_b32_e32 v8, v128
	v_mov_b32_e32 v9, v129
	v_mov_b32_e32 v10, v130
	v_mov_b32_e32 v11, v131
	s_nop 0
	v_mov_b32_e32 v38, v132
	v_mov_b32_e32 v39, v133
	v_mov_b32_e32 v40, v134
	v_mov_b32_e32 v41, v135
	v_lshlrev_b32_e32 v46, 16, v37
	v_and_b32_e32 v37, 0xffff0000, v36
	v_lshlrev_b32_e32 v36, 16, v36
	v_add_f32_e32 v50, v50, v52
	v_pk_mul_f32 v[14:15], v[36:37], v[36:37]
	v_add_f32_e32 v50, v51, v50
	v_add_f32_e32 v14, v14, v50
	v_pk_mul_f32 v[12:13], v[46:47], v[46:47]
	v_add_f32_e32 v14, v15, v14
	v_add_f32_e32 v12, v12, v14
	v_add_f32_e32 v12, v13, v12
	ds_swizzle_b32 v13, v12 offset:swizzle(SWAP,1)
	v_div_scale_f32 v57, vcc, 1.0, v54, 1.0
	v_mul_f32_e32 v58, v57, v56
	v_fma_f32 v59, -v55, v58, v57
	s_waitcnt lgkmcnt(0)
	v_add_f32_e32 v15, v12, v13
	ds_swizzle_b32 v51, v15 offset:swizzle(SWAP,2)
	v_fmac_f32_e32 v58, v59, v56
	v_fma_f32 v14, -v55, v58, v57
	v_div_fmas_f32 v14, v14, v56, v58
	v_div_fixup_f32 v50, v14, v54, 1.0
	s_waitcnt lgkmcnt(0)
	v_pk_mul_f32 v[12:13], v[50:51], v[44:45] op_sel_hi:[0,1]
	v_add_f32_e32 v44, v15, v51
	ds_swizzle_b32 v45, v44 offset:swizzle(SWAP,4)
	v_pk_mul_f32 v[14:15], v[50:51], v[42:43] op_sel_hi:[0,1]
	v_pk_mul_f32 v[12:13], v[4:5], v[12:13]
	v_pk_mul_f32 v[14:15], v[6:7], v[14:15]
	v_cvt_pk_bf16_f32 v12, v12, v13
	v_cvt_pk_bf16_f32 v13, v14, v15
	v_pk_mul_f32 v[14:15], v[50:51], v[28:29] op_sel_hi:[0,1]
	s_waitcnt lgkmcnt(0)
	v_add_f32_e32 v28, v44, v45
	ds_swizzle_b32 v29, v28 offset:swizzle(SWAP,8)
	v_pk_mul_f32 v[14:15], v[0:1], v[14:15]
	v_pk_mul_f32 v[26:27], v[50:51], v[26:27] op_sel_hi:[0,1]
	v_cvt_pk_bf16_f32 v14, v14, v15
	v_pk_mul_f32 v[26:27], v[2:3], v[26:27]
	s_waitcnt lgkmcnt(0)
	v_add_f32_e32 v15, v28, v29
	v_fmamk_f32 v15, v15, 0x3c000000, v224
	v_mul_f32_e32 v28, 0x4f800000, v15
	v_cmp_gt_f32_e32 vcc, s18, v15
	s_nop 0
	v_and_b32_e32 v51, 0xffff0000, v38
	v_cndmask_b32_e32 v28, v15, v28, vcc
	v_sqrt_f32_e32 v29, v28
	v_cvt_pk_bf16_f32 v15, v26, v27
	ds_write_b128 v30, v[12:15] offset:32768
	ds_write_b128 v31, v[20:23] offset:32768
	v_lshlrev_b32_e32 v50, 16, v38
	v_add_u32_e32 v12, -1, v29
	v_fma_f32 v13, -v12, v29, v28
	v_cmp_ge_f32_e64 s[36:37], 0, v13
	v_add_u32_e32 v13, 1, v29
	v_fma_f32 v14, -v13, v29, v28
	v_cndmask_b32_e64 v12, v29, v12, s[36:37]
	v_cmp_lt_f32_e64 s[36:37], 0, v14
	v_and_b32_e32 v45, 0xffff0000, v39
	v_lshlrev_b32_e32 v44, 16, v39
	v_cndmask_b32_e64 v12, v12, v13, s[36:37]
	v_mul_f32_e32 v13, 0x37800000, v12
	v_cndmask_b32_e32 v12, v12, v13, vcc
	v_cmp_class_f32_e32 vcc, v28, v250
	v_pk_mul_f32 v[38:39], v[50:51], v[50:51]
	v_and_b32_e32 v29, 0xffff0000, v41
	v_cndmask_b32_e32 v52, v12, v28, vcc
	v_div_scale_f32 v53, s[8:9], v52, v52, 1.0
	s_mov_b64 s[8:9], 0x1c0000
	s_nop 0
	v_lshl_add_u64 v[12:13], v[24:25], 0, s[8:9]
	s_mov_b32 s8, 0x1c0000
	v_add_co_u32_e32 v20, vcc, s8, v24
	v_rcp_f32_e32 v54, v53
	s_nop 0
	v_addc_co_u32_e32 v21, vcc, 0, v25, vcc
	s_waitcnt vmcnt(0)
	v_mov_b32_e32 v12, v136
	v_mov_b32_e32 v13, v137
	v_mov_b32_e32 v14, v138
	v_mov_b32_e32 v15, v139
	s_nop 0
	v_mov_b32_e32 v20, v140
	v_mov_b32_e32 v21, v141
	v_mov_b32_e32 v22, v142
	v_mov_b32_e32 v23, v143
	v_lshlrev_b32_e32 v28, 16, v41
	v_and_b32_e32 v43, 0xffff0000, v40
	v_lshlrev_b32_e32 v42, 16, v40
	v_pk_mul_f32 v[40:41], v[44:45], v[44:45]
	v_add_f32_e32 v38, v38, v39
	v_add_f32_e32 v38, v40, v38
	v_pk_mul_f32 v[26:27], v[42:43], v[42:43]
	v_add_f32_e32 v38, v41, v38
	v_fma_f32 v24, -v53, v54, 1.0
	v_add_f32_e32 v26, v26, v38
	v_fmac_f32_e32 v54, v24, v54
	v_pk_mul_f32 v[24:25], v[28:29], v[28:29]
	v_add_f32_e32 v26, v27, v26
	v_add_f32_e32 v24, v24, v26
	v_add_f32_e32 v24, v25, v24
	ds_swizzle_b32 v25, v24 offset:swizzle(SWAP,1)
	v_div_scale_f32 v26, vcc, 1.0, v52, 1.0
	v_mul_f32_e32 v27, v26, v54
	v_fma_f32 v38, -v53, v27, v26
	s_waitcnt lgkmcnt(0)
; template <int X> __device__ __forceinline__ float swz_xor(float v) { return __int_as_float(__builtin_amdgcn_ds_swizzle(__float_as_int(v), (X << 10) | 0x1f)); }
; __device__ __forceinline__ unsigned cvtpk(float lo, float hi) { f32x2_t v = {lo, hi}; bf16x2_t b = __builtin_convertvector(v, bf16x2_t); return __builtin_bit_cast(unsigned, b); }
; __device__ __forceinline__ float bf2f(unsigned short h) { return __uint_as_float(((unsigned)h) << 16); }
; __device__ __forceinline__ void mem_unit(const MemArgs& A, int unit, char* lds, int wv) {
;     ...
;     { const int sr = tid >> 4, sc = (tid & 15) * 8, kc = sc * 2;
;       const f32x4 g0 = *(const f32x4*)(A.gmk + sc), g1 = *(const f32x4*)(A.gmk + sc + 4);
; #pragma unroll
;       for (int t = 0; t < 4; ++t)
; #pragma unroll
;         for (int hh = 0; hh < 2; ++hh) { const int key = t * 64 + hh * 32 + sr;
;           const bf16x8 v8 = *reinterpret_cast<const bf16x8*>(&Vh[(size_t)key * MKVC + sc]); const bf16x8 k8 = *reinterpret_cast<const bf16x8*>(&Kh[(size_t)key * MKVC + sc]);
;           float f[8]; float ss = 0.f;
; #pragma unroll
;           for (int i = 0; i < 8; ++i) { f[i] = bf2f((unsigned short)k8[i]); ss += f[i] * f[i]; }
;           ss += swz_xor<1>(ss); ss += swz_xor<2>(ss); ss += swz_xor<4>(ss); ss += swz_xor<8>(ss);
;           const float rn = 1.0f / sqrtf(ss * (1.0f / 128.0f) + EPS);
;           u32x4 w; w.x = cvtpk(f[0] * rn * g0.x, f[1] * rn * g0.y); w.y = cvtpk(f[2] * rn * g0.z, f[3] * rn * g0.w); w.z = cvtpk(f[4] * rn * g1.x, f[5] * rn * g1.y); w.w = cvtpk(f[6] * rn * g1.z, f[7] * rn * g1.w);
;           *(u32x4*)(K_lds + t * SHM_K + KSWZ(hh * 32 + sr, kc)) = w;
;           { const int ks_ = hh * 32 + sr, kp_ = (ks_ & ~0xC) | ((ks_ & 4) << 1) | ((ks_ & 8) >> 1);
;             *(bf16x8*)(V_lds + t * SHM_V + v_st(kp_, sc)) = v8; } } }
;     bf16x8 qr[8];
;     const size_t grow0 = (size_t)b * SEQ + qb * 256 + wid * 32;
;     { const bf16* Qw = A.proj + (grow0 + r32) * INC + C_MQ + hm * 128 + hi * 8;
;       bf16x8 raw[8]; float ss = 0.f;
; #pragma unroll
;       for (int d0 = 0; d0 < 8; ++d0) { raw[d0] = *reinterpret_cast<const bf16x8*>(Qw + d0 * 16);
; #pragma unroll
;           for (int i = 0; i < 8; ++i) { const float f = bf2f((unsigned short)raw[d0][i]); ss += f * f; } }
	v_add_f32_e32 v24, v24, v25
	ds_swizzle_b32 v25, v24 offset:swizzle(SWAP,2)
	v_fmac_f32_e32 v27, v38, v54
	v_fma_f32 v26, -v53, v27, v26
	v_div_fmas_f32 v26, v26, v54, v27
	v_div_fixup_f32 v38, v26, v52, 1.0
	s_waitcnt lgkmcnt(0)
	v_add_f32_e32 v39, v24, v25
	ds_swizzle_b32 v40, v39 offset:swizzle(SWAP,4)
	v_pk_mul_f32 v[24:25], v[38:39], v[34:35] op_sel_hi:[0,1]
	v_pk_mul_f32 v[26:27], v[38:39], v[48:49] op_sel_hi:[0,1]
	v_pk_mul_f32 v[24:25], v[4:5], v[24:25]
	v_pk_mul_f32 v[26:27], v[6:7], v[26:27]
	s_waitcnt lgkmcnt(0)
	v_add_f32_e32 v34, v39, v40
	ds_swizzle_b32 v35, v34 offset:swizzle(SWAP,8)
	v_cvt_pk_bf16_f32 v24, v24, v25
	v_cvt_pk_bf16_f32 v25, v26, v27
	v_pk_mul_f32 v[26:27], v[38:39], v[36:37] op_sel_hi:[0,1]
	v_pk_mul_f32 v[26:27], v[0:1], v[26:27]
	s_waitcnt lgkmcnt(0)
	v_add_f32_e32 v34, v34, v35
	v_fmamk_f32 v34, v34, 0x3c000000, v224
	v_mul_f32_e32 v35, 0x4f800000, v34
	v_cmp_gt_f32_e32 vcc, s18, v34
	v_cvt_pk_bf16_f32 v26, v26, v27
	s_nop 0
	v_cndmask_b32_e32 v36, v34, v35, vcc
	v_sqrt_f32_e32 v37, v36
	v_pk_mul_f32 v[34:35], v[38:39], v[46:47] op_sel_hi:[0,1]
	v_pk_mul_f32 v[34:35], v[2:3], v[34:35]
	v_add_u32_e32 v27, -1, v37
	v_fma_f32 v38, -v27, v37, v36
	v_cmp_ge_f32_e64 s[36:37], 0, v38
	v_add_u32_e32 v38, 1, v37
	s_nop 0
	v_cndmask_b32_e64 v27, v37, v27, s[36:37]
	v_fma_f32 v37, -v38, v37, v36
	v_cmp_lt_f32_e64 s[36:37], 0, v37
	s_nop 1
	v_cndmask_b32_e64 v27, v27, v38, s[36:37]
	v_mul_f32_e32 v37, 0x37800000, v27
	v_cndmask_b32_e32 v27, v27, v37, vcc
	v_cmp_class_f32_e32 vcc, v36, v250
	s_nop 1
	v_cndmask_b32_e32 v38, v27, v36, vcc
	v_div_scale_f32 v39, s[8:9], v38, v38, 1.0
	v_rcp_f32_e32 v40, v39
	v_cvt_pk_bf16_f32 v27, v34, v35
	ds_write_b128 v32, v[24:27] offset:32768
	ds_write_b128 v33, v[16:19] offset:32768
	v_div_scale_f32 v41, vcc, 1.0, v38, 1.0
	v_fma_f32 v16, -v39, v40, 1.0
	v_fmac_f32_e32 v40, v16, v40
	v_mul_f32_e32 v46, v41, v40
	v_fma_f32 v16, -v39, v46, v41
	v_fmac_f32_e32 v46, v16, v40
	s_lshl_b64 s[8:9], s[84:85], 13
	s_nop 0
	v_and_b32_e32 v27, 0xffff0000, v21
	v_lshlrev_b32_e32 v26, 16, v21
	v_and_b32_e32 v21, 0xffff0000, v20
	v_lshlrev_b32_e32 v20, 16, v20
	v_pk_mul_f32 v[36:37], v[20:21], v[20:21]
	v_pk_mul_f32 v[34:35], v[26:27], v[26:27]
	v_add_f32_e32 v36, v36, v37
	v_and_b32_e32 v25, 0xffff0000, v23
	v_lshlrev_b32_e32 v24, 16, v23
	v_and_b32_e32 v23, 0xffff0000, v22
	v_lshlrev_b32_e32 v22, 16, v22
	v_add_f32_e32 v34, v34, v36
	v_pk_mul_f32 v[18:19], v[22:23], v[22:23]
	v_add_f32_e32 v34, v35, v34
	v_add_f32_e32 v18, v18, v34
	v_pk_mul_f32 v[16:17], v[24:25], v[24:25]
	v_add_f32_e32 v18, v19, v18
	v_add_f32_e32 v16, v16, v18
	v_add_f32_e32 v16, v17, v16
	ds_swizzle_b32 v17, v16 offset:swizzle(SWAP,1)
	s_or_b32 s3, s8, s3
	s_ashr_i32 s8, s1, 1
	s_andn2_b32 s8, s8, 31
	v_fma_f32 v18, -v39, v46, v41
	s_ashr_i32 s16, s8, 31
	v_div_fmas_f32 v18, v18, v40, v46
	s_add_u32 s8, s3, s8
	v_div_fixup_f32 v34, v18, v38, 1.0
	s_waitcnt lgkmcnt(0)
	v_add_f32_e32 v35, v16, v17
	v_or_b32_e32 v18, s8, v144
	v_mov_b64_e32 v[16:17], s[80:81]
	s_addc_u32 s3, s9, s16
	v_mad_u64_u32 v[16:17], s[16:17], v18, s33, v[16:17]
	v_mov_b32_e32 v18, 0x3800
	v_mad_i32_i24 v17, s3, v18, v17
	v_lshl_add_u64 v[16:17], v[16:17], 0, s[6:7]
	v_lshl_add_u64 v[16:17], v[16:17], 0, v[176:177]
	s_mov_b64 s[6:7], 0x3000
	v_lshl_add_u64 v[36:37], v[16:17], 0, s[6:7]
	v_add_co_u32_e32 v16, vcc, s63, v16
	ds_swizzle_b32 v46, v35 offset:swizzle(SWAP,2)
	s_nop 0
	v_addc_co_u32_e32 v17, vcc, 0, v17, vcc
	global_load_dwordx4 v[80:83], v[16:17], off
	global_load_dwordx4 v[38:41], v[36:37], off offset:224
	v_pk_mul_f32 v[16:17], v[34:35], v[50:51] op_sel_hi:[0,1]
	v_pk_mul_f32 v[18:19], v[34:35], v[44:45] op_sel_hi:[0,1]
	s_waitcnt lgkmcnt(0)
	v_add_f32_e32 v35, v35, v46
	global_load_dwordx4 v[54:57], v[36:37], off offset:160
	global_load_dwordx4 v[46:49], v[36:37], off offset:192
	global_load_dwordx4 v[70:73], v[36:37], off offset:96
	global_load_dwordx4 v[62:65], v[36:37], off offset:128
	global_load_dwordx4 v[84:87], v[36:37], off offset:32
	global_load_dwordx4 v[88:91], v[36:37], off offset:64
	ds_swizzle_b32 v44, v35 offset:swizzle(SWAP,4)
	v_pk_mul_f32 v[16:17], v[4:5], v[16:17]
	v_pk_mul_f32 v[18:19], v[6:7], v[18:19]
	v_cvt_pk_bf16_f32 v16, v16, v17
	v_cvt_pk_bf16_f32 v17, v18, v19
	s_waitcnt lgkmcnt(0)
	v_add_f32_e32 v35, v35, v44
	ds_swizzle_b32 v44, v35 offset:swizzle(SWAP,8)
	v_pk_mul_f32 v[18:19], v[34:35], v[42:43] op_sel_hi:[0,1]
	v_pk_mul_f32 v[18:19], v[0:1], v[18:19]
	v_pk_mul_f32 v[28:29], v[34:35], v[28:29] op_sel_hi:[0,1]
	v_cvt_pk_bf16_f32 v18, v18, v19
	s_waitcnt lgkmcnt(0)
	v_add_f32_e32 v19, v35, v44
	v_fmamk_f32 v19, v19, 0x3c000000, v224
	v_mul_f32_e32 v34, 0x4f800000, v19
	v_cmp_gt_f32_e32 vcc, s18, v19
	v_pk_mul_f32 v[28:29], v[2:3], v[28:29]
	s_mov_b32 s9, 0x3e0293ee
	v_cndmask_b32_e32 v19, v19, v34, vcc
	v_sqrt_f32_e32 v34, v19
	s_cmp_lg_u32 0, -1
	v_add_u32_e32 v35, -1, v34
	v_fma_f32 v42, -v35, v34, v19
	v_cmp_ge_f32_e64 s[36:37], 0, v42
	v_add_u32_e32 v42, 1, v34
	s_waitcnt vmcnt(7)
; template <int X> __device__ __forceinline__ float swz_xor(float v) { return __int_as_float(__builtin_amdgcn_ds_swizzle(__float_as_int(v), (X << 10) | 0x1f)); }
; __device__ __forceinline__ unsigned cvtpk(float lo, float hi) { f32x2_t v = {lo, hi}; bf16x2_t b = __builtin_convertvector(v, bf16x2_t); return __builtin_bit_cast(unsigned, b); }
; __device__ __forceinline__ float bf2f(unsigned short h) { return __uint_as_float(((unsigned)h) << 16); }
; __device__ __forceinline__ int v_st(int k, int c) { const int kk = (k & ~0xC) | ((k & 4) << 1) | ((k & 8) >> 1); return ((kk >> 3) * 4 + (c >> 5)) * 512 + ((kk & 7) * 32 + (c & 31)) * 2; }
; __device__ __forceinline__ void mem_unit(const MemArgs& A, int unit, char* lds, int wv) {
;     ...
;           for (int i = 0; i < 8; ++i) { f[i] = bf2f((unsigned short)k8[i]); ss += f[i] * f[i]; }
;           ss += swz_xor<1>(ss); ss += swz_xor<2>(ss); ss += swz_xor<4>(ss); ss += swz_xor<8>(ss);
;           const float rn = 1.0f / sqrtf(ss * (1.0f / 128.0f) + EPS);
;           u32x4 w; w.x = cvtpk(f[0] * rn * g0.x, f[1] * rn * g0.y); w.y = cvtpk(f[2] * rn * g0.z, f[3] * rn * g0.w); w.z = cvtpk(f[4] * rn * g1.x, f[5] * rn * g1.y); w.w = cvtpk(f[6] * rn * g1.z, f[7] * rn * g1.w);
;           *(u32x4*)(K_lds + t * SHM_K + KSWZ(hh * 32 + sr, kc)) = w;
;           { const int ks_ = hh * 32 + sr, kp_ = (ks_ & ~0xC) | ((ks_ & 4) << 1) | ((ks_ & 8) >> 1);
;             *(bf16x8*)(V_lds + t * SHM_V + v_st(kp_, sc)) = v8; } } }
;     bf16x8 qr[8];
;     const size_t grow0 = (size_t)b * SEQ + qb * 256 + wid * 32;
;     { const bf16* Qw = A.proj + (grow0 + r32) * INC + C_MQ + hm * 128 + hi * 8;
;       bf16x8 raw[8]; float ss = 0.f;
; #pragma unroll
;       for (int d0 = 0; d0 < 8; ++d0) { raw[d0] = *reinterpret_cast<const bf16x8*>(Qw + d0 * 16);
; #pragma unroll
;           for (int i = 0; i < 8; ++i) { const float f = bf2f((unsigned short)raw[d0][i]); ss += f * f; } }
	v_and_b32_e32 v113, 0xffff0000, v80
	v_cndmask_b32_e64 v35, v34, v35, s[36:37]
	v_fma_f32 v34, -v42, v34, v19
	v_cmp_lt_f32_e64 s[36:37], 0, v34
	v_lshlrev_b32_e32 v112, 16, v80
	v_mul_f32_e32 v80, v113, v113
	v_cndmask_b32_e64 v34, v35, v42, s[36:37]
	v_mul_f32_e32 v35, 0x37800000, v34
	v_cndmask_b32_e32 v34, v34, v35, vcc
	v_cmp_class_f32_e32 vcc, v19, v250
	v_and_b32_e32 v129, 0xffff0000, v81
	v_lshlrev_b32_e32 v128, 16, v81
	v_cndmask_b32_e32 v34, v34, v19, vcc
	v_div_scale_f32 v35, s[6:7], v34, v34, 1.0
	v_rcp_f32_e32 v36, v35
	v_pk_fma_f32 v[80:81], v[112:113], v[112:113], v[80:81] op_sel_hi:[1,1,0]
	v_and_b32_e32 v115, 0xffff0000, v82
	v_lshlrev_b32_e32 v114, 16, v82
	v_pk_fma_f32 v[80:81], v[128:129], v[128:129], v[80:81]
	v_mul_f32_e32 v82, v129, v129
	v_pk_add_f32 v[80:81], v[82:83], v[80:81] op_sel_hi:[0,1]
	v_cvt_pk_bf16_f32 v19, v28, v29
	v_pk_fma_f32 v[80:81], v[114:115], v[114:115], v[80:81]
	v_mul_f32_e32 v82, v115, v115
	ds_write_b128 v30, v[16:19] offset:49152
	ds_write_b128 v31, v[8:11] offset:49152
	v_fma_f32 v8, -v35, v36, 1.0
	v_and_b32_e32 v127, 0xffff0000, v83
	v_lshlrev_b32_e32 v126, 16, v83
	v_pk_add_f32 v[80:81], v[82:83], v[80:81] op_sel_hi:[0,1]
	v_fmac_f32_e32 v36, v8, v36
	v_div_scale_f32 v8, vcc, 1.0, v34, 1.0
	v_pk_fma_f32 v[80:81], v[126:127], v[126:127], v[80:81]
	v_mul_f32_e32 v82, v127, v127
	v_mul_f32_e32 v9, v8, v36
	s_waitcnt vmcnt(1)
	v_and_b32_e32 v117, 0xffff0000, v84
	v_lshlrev_b32_e32 v116, 16, v84
	v_pk_add_f32 v[80:81], v[82:83], v[80:81] op_sel_hi:[0,1]
	v_fma_f32 v10, -v35, v9, v8
	v_pk_fma_f32 v[80:81], v[116:117], v[116:117], v[80:81]
	v_mul_f32_e32 v82, v117, v117
	v_fmac_f32_e32 v9, v10, v36
	v_and_b32_e32 v125, 0xffff0000, v85
	v_lshlrev_b32_e32 v124, 16, v85
	v_pk_add_f32 v[80:81], v[82:83], v[80:81] op_sel_hi:[0,1]
	v_fma_f32 v8, -v35, v9, v8
	v_pk_fma_f32 v[80:81], v[124:125], v[124:125], v[80:81]
	v_mul_f32_e32 v82, v125, v125
	v_div_fmas_f32 v8, v8, v36, v9
	v_and_b32_e32 v119, 0xffff0000, v86
	v_lshlrev_b32_e32 v118, 16, v86
	v_pk_add_f32 v[80:81], v[82:83], v[80:81] op_sel_hi:[0,1]
	v_div_fixup_f32 v8, v8, v34, 1.0
	v_pk_fma_f32 v[80:81], v[118:119], v[118:119], v[80:81]
	v_mul_f32_e32 v82, v119, v119
	v_pk_mul_f32 v[10:11], v[8:9], v[20:21] op_sel_hi:[0,1]
	v_and_b32_e32 v123, 0xffff0000, v87
	v_lshlrev_b32_e32 v122, 16, v87
	v_pk_add_f32 v[80:81], v[82:83], v[80:81] op_sel_hi:[0,1]
	v_pk_mul_f32 v[4:5], v[4:5], v[10:11]
	v_pk_mul_f32 v[10:11], v[8:9], v[26:27] op_sel_hi:[0,1]
	v_pk_fma_f32 v[80:81], v[122:123], v[122:123], v[80:81]
	v_mul_f32_e32 v82, v123, v123
	v_pk_mul_f32 v[6:7], v[6:7], v[10:11]
	s_waitcnt vmcnt(0)
	v_and_b32_e32 v121, 0xffff0000, v88
	v_lshlrev_b32_e32 v120, 16, v88
	v_pk_add_f32 v[80:81], v[82:83], v[80:81] op_sel_hi:[0,1]
	v_cvt_pk_bf16_f32 v4, v4, v5
	v_cvt_pk_bf16_f32 v5, v6, v7
	v_pk_mul_f32 v[6:7], v[8:9], v[22:23] op_sel_hi:[0,1]
	v_pk_fma_f32 v[80:81], v[120:121], v[120:121], v[80:81]
	v_mul_f32_e32 v82, v121, v121
	v_pk_mul_f32 v[0:1], v[0:1], v[6:7]
	v_and_b32_e32 v77, 0xffff0000, v89
	v_lshlrev_b32_e32 v76, 16, v89
	v_pk_add_f32 v[80:81], v[82:83], v[80:81] op_sel_hi:[0,1]
	v_cvt_pk_bf16_f32 v6, v0, v1
	v_pk_mul_f32 v[0:1], v[8:9], v[24:25] op_sel_hi:[0,1]
	v_pk_fma_f32 v[80:81], v[76:77], v[76:77], v[80:81]
	v_mul_f32_e32 v82, v77, v77
	v_pk_mul_f32 v[0:1], v[2:3], v[0:1]
	v_and_b32_e32 v75, 0xffff0000, v90
	v_lshlrev_b32_e32 v74, 16, v90
	v_pk_add_f32 v[80:81], v[82:83], v[80:81] op_sel_hi:[0,1]
	v_cvt_pk_bf16_f32 v7, v0, v1
	v_pk_fma_f32 v[80:81], v[74:75], v[74:75], v[80:81]
	v_mul_f32_e32 v82, v75, v75
	ds_write_b128 v32, v[4:7] offset:49152
	ds_write_b128 v33, v[12:15] offset:49152
	v_and_b32_e32 v33, 0xffff0000, v41
	v_lshlrev_b32_e32 v32, 16, v41
	v_and_b32_e32 v35, 0xffff0000, v40
	v_lshlrev_b32_e32 v34, 16, v40
	v_and_b32_e32 v41, 0xffff0000, v49
	v_lshlrev_b32_e32 v40, 16, v49
	v_and_b32_e32 v43, 0xffff0000, v48
	v_lshlrev_b32_e32 v42, 16, v48
	v_and_b32_e32 v49, 0xffff0000, v57
	v_lshlrev_b32_e32 v48, 16, v57
	v_and_b32_e32 v51, 0xffff0000, v56
	v_lshlrev_b32_e32 v50, 16, v56
	v_and_b32_e32 v57, 0xffff0000, v65
	v_lshlrev_b32_e32 v56, 16, v65
	v_and_b32_e32 v59, 0xffff0000, v64
	v_lshlrev_b32_e32 v58, 16, v64
	v_and_b32_e32 v65, 0xffff0000, v73
	v_lshlrev_b32_e32 v64, 16, v73
	v_and_b32_e32 v67, 0xffff0000, v72
	v_lshlrev_b32_e32 v66, 16, v72
	v_and_b32_e32 v73, 0xffff0000, v91
	v_lshlrev_b32_e32 v72, 16, v91
	v_pk_add_f32 v[80:81], v[82:83], v[80:81] op_sel_hi:[0,1]
	v_pk_fma_f32 v[80:81], v[72:73], v[72:73], v[80:81]
	v_mul_f32_e32 v82, v73, v73
	v_and_b32_e32 v69, 0xffff0000, v71
	v_lshlrev_b32_e32 v68, 16, v71
	v_and_b32_e32 v71, 0xffff0000, v70
	v_lshlrev_b32_e32 v70, 16, v70
	v_pk_add_f32 v[80:81], v[82:83], v[80:81] op_sel_hi:[0,1]
	v_pk_fma_f32 v[80:81], v[70:71], v[70:71], v[80:81]
	v_mul_f32_e32 v82, v71, v71
	v_pk_add_f32 v[80:81], v[82:83], v[80:81] op_sel_hi:[0,1]
	v_pk_fma_f32 v[80:81], v[68:69], v[68:69], v[80:81]
	v_mul_f32_e32 v82, v69, v69
	v_pk_add_f32 v[80:81], v[82:83], v[80:81] op_sel_hi:[0,1]
	v_pk_fma_f32 v[80:81], v[66:67], v[66:67], v[80:81]
	v_mul_f32_e32 v82, v67, v67
	v_pk_add_f32 v[80:81], v[82:83], v[80:81] op_sel_hi:[0,1]
	v_pk_fma_f32 v[80:81], v[64:65], v[64:65], v[80:81]
	v_mul_f32_e32 v82, v65, v65
	v_and_b32_e32 v61, 0xffff0000, v63
	v_lshlrev_b32_e32 v60, 16, v63
	v_and_b32_e32 v63, 0xffff0000, v62
	v_lshlrev_b32_e32 v62, 16, v62
	v_pk_add_f32 v[80:81], v[82:83], v[80:81] op_sel_hi:[0,1]
	v_pk_fma_f32 v[80:81], v[62:63], v[62:63], v[80:81]
	v_mul_f32_e32 v82, v63, v63
	v_pk_add_f32 v[80:81], v[82:83], v[80:81] op_sel_hi:[0,1]
	v_pk_fma_f32 v[80:81], v[60:61], v[60:61], v[80:81]
; __device__ __forceinline__ unsigned cvtpk(float lo, float hi) { f32x2_t v = {lo, hi}; bf16x2_t b = __builtin_convertvector(v, bf16x2_t); return __builtin_bit_cast(unsigned, b); }
; __device__ __forceinline__ float bf2f(unsigned short h) { return __uint_as_float(((unsigned)h) << 16); }
; __device__ __forceinline__ void mem_unit(const MemArgs& A, int unit, char* lds, int wv) {
;     ...
;     { const bf16* Qw = A.proj + (grow0 + r32) * INC + C_MQ + hm * 128 + hi * 8;
;       bf16x8 raw[8]; float ss = 0.f;
; #pragma unroll
;       for (int d0 = 0; d0 < 8; ++d0) { raw[d0] = *reinterpret_cast<const bf16x8*>(Qw + d0 * 16);
; #pragma unroll
;           for (int i = 0; i < 8; ++i) { const float f = bf2f((unsigned short)raw[d0][i]); ss += f * f; } }
;       { auto rr = __builtin_amdgcn_permlane32_swap(__float_as_uint(ss), __float_as_uint(ss), false, false); ss = __uint_as_float(rr[0]) + __uint_as_float(rr[1]); }
;       const float rn = QSCALE_M / sqrtf(ss * (1.0f / 128.0f) + EPS);
; #pragma unroll
;       for (int d0 = 0; d0 < 8; ++d0) { const f32x4 g0 = *(const f32x4*)(A.gmq + d0 * 16 + hi * 8), g1 = *(const f32x4*)(A.gmq + d0 * 16 + hi * 8 + 4);
;           u32x4 w; w.x = cvtpk(bf2f((unsigned short)raw[d0][0]) * rn * g0.x, bf2f((unsigned short)raw[d0][1]) * rn * g0.y); w.y = cvtpk(bf2f((unsigned short)raw[d0][2]) * rn * g0.z, bf2f((unsigned short)raw[d0][3]) * rn * g0.w);
;           w.z = cvtpk(bf2f((unsigned short)raw[d0][4]) * rn * g1.x, bf2f((unsigned short)raw[d0][5]) * rn * g1.y); w.w = cvtpk(bf2f((unsigned short)raw[d0][6]) * rn * g1.z, bf2f((unsigned short)raw[d0][7]) * rn * g1.w);
;           qr[d0] = *reinterpret_cast<bf16x8*>(&w); } }
;     __syncthreads();
	v_mul_f32_e32 v82, v61, v61
	v_pk_add_f32 v[80:81], v[82:83], v[80:81] op_sel_hi:[0,1]
	v_pk_fma_f32 v[80:81], v[58:59], v[58:59], v[80:81]
	v_mul_f32_e32 v82, v59, v59
	v_pk_add_f32 v[80:81], v[82:83], v[80:81] op_sel_hi:[0,1]
	v_pk_fma_f32 v[80:81], v[56:57], v[56:57], v[80:81]
	v_mul_f32_e32 v82, v57, v57
	v_and_b32_e32 v53, 0xffff0000, v55
	v_lshlrev_b32_e32 v52, 16, v55
	v_and_b32_e32 v55, 0xffff0000, v54
	v_lshlrev_b32_e32 v54, 16, v54
	v_pk_add_f32 v[80:81], v[82:83], v[80:81] op_sel_hi:[0,1]
	v_pk_fma_f32 v[80:81], v[54:55], v[54:55], v[80:81]
	v_mul_f32_e32 v82, v55, v55
	global_load_dwordx4 v[24:27], v108, s[40:41] offset:16
	global_load_dwordx4 v[28:31], v108, s[40:41]
	global_load_dwordx4 v[16:19], v108, s[40:41] offset:80
	global_load_dwordx4 v[20:23], v108, s[40:41] offset:64
	global_load_dwordx4 v[8:11], v108, s[40:41] offset:144
	global_load_dwordx4 v[12:15], v108, s[40:41] offset:128
	global_load_dwordx4 v[0:3], v108, s[40:41] offset:208
	global_load_dwordx4 v[4:7], v108, s[40:41] offset:192
	v_pk_add_f32 v[80:81], v[82:83], v[80:81] op_sel_hi:[0,1]
	v_pk_fma_f32 v[80:81], v[52:53], v[52:53], v[80:81]
	v_mul_f32_e32 v82, v53, v53
	v_pk_add_f32 v[80:81], v[82:83], v[80:81] op_sel_hi:[0,1]
	v_pk_fma_f32 v[80:81], v[50:51], v[50:51], v[80:81]
	v_mul_f32_e32 v82, v51, v51
	v_pk_add_f32 v[80:81], v[82:83], v[80:81] op_sel_hi:[0,1]
	v_pk_fma_f32 v[80:81], v[48:49], v[48:49], v[80:81]
	v_mul_f32_e32 v82, v49, v49
	v_and_b32_e32 v45, 0xffff0000, v47
	v_lshlrev_b32_e32 v44, 16, v47
	v_and_b32_e32 v47, 0xffff0000, v46
	v_lshlrev_b32_e32 v46, 16, v46
	v_pk_add_f32 v[80:81], v[82:83], v[80:81] op_sel_hi:[0,1]
	v_pk_fma_f32 v[80:81], v[46:47], v[46:47], v[80:81]
	v_mul_f32_e32 v82, v47, v47
	v_pk_add_f32 v[80:81], v[82:83], v[80:81] op_sel_hi:[0,1]
	v_pk_fma_f32 v[80:81], v[44:45], v[44:45], v[80:81]
	v_mul_f32_e32 v82, v45, v45
	v_pk_add_f32 v[80:81], v[82:83], v[80:81] op_sel_hi:[0,1]
	v_pk_fma_f32 v[80:81], v[42:43], v[42:43], v[80:81]
	v_mul_f32_e32 v82, v43, v43
	v_pk_add_f32 v[80:81], v[82:83], v[80:81] op_sel_hi:[0,1]
	v_pk_fma_f32 v[80:81], v[40:41], v[40:41], v[80:81]
	v_mul_f32_e32 v82, v41, v41
	v_and_b32_e32 v37, 0xffff0000, v39
	v_lshlrev_b32_e32 v36, 16, v39
	v_and_b32_e32 v39, 0xffff0000, v38
	v_lshlrev_b32_e32 v38, 16, v38
	v_pk_add_f32 v[80:81], v[82:83], v[80:81] op_sel_hi:[0,1]
	v_pk_fma_f32 v[80:81], v[38:39], v[38:39], v[80:81]
	v_mul_f32_e32 v82, v39, v39
	v_pk_add_f32 v[80:81], v[82:83], v[80:81] op_sel_hi:[0,1]
	v_pk_fma_f32 v[80:81], v[36:37], v[36:37], v[80:81]
	v_mul_f32_e32 v82, v37, v37
	v_pk_add_f32 v[80:81], v[82:83], v[80:81] op_sel_hi:[0,1]
	v_pk_fma_f32 v[80:81], v[34:35], v[34:35], v[80:81]
	v_mul_f32_e32 v82, v35, v35
	v_pk_add_f32 v[80:81], v[82:83], v[80:81] op_sel_hi:[0,1]
	v_pk_fma_f32 v[80:81], v[32:33], v[32:33], v[80:81]
	v_mul_f32_e32 v82, v33, v33
	v_pk_add_f32 v[80:81], v[82:83], v[80:81] op_sel_hi:[0,1]
	v_mov_b32_e32 v81, v80
	s_nop 1
	v_permlane32_swap_b32_e32 v80, v81
	v_add_f32_e32 v80, v80, v81
	v_fmamk_f32 v80, v80, 0x3c000000, v224
	v_mul_f32_e32 v81, 0x4f800000, v80
	v_cmp_gt_f32_e32 vcc, s18, v80
	s_nop 1
	v_cndmask_b32_e32 v96, v80, v81, vcc
	global_load_dwordx4 v[80:83], v108, s[40:41] offset:272
	global_load_dwordx4 v[84:87], v108, s[40:41] offset:256
	global_load_dwordx4 v[88:91], v108, s[40:41] offset:336
	global_load_dwordx4 v[92:95], v108, s[40:41] offset:320
	v_sqrt_f32_e32 v97, v96
	s_nop 0
	v_add_u32_e32 v98, -1, v97
	v_fma_f32 v99, -v98, v97, v96
	v_cmp_ge_f32_e64 s[36:37], 0, v99
	v_add_u32_e32 v99, 1, v97
	s_nop 0
	v_cndmask_b32_e64 v98, v97, v98, s[36:37]
	v_fma_f32 v97, -v99, v97, v96
	v_cmp_lt_f32_e64 s[36:37], 0, v97
	s_nop 1
	v_cndmask_b32_e64 v97, v98, v99, s[36:37]
	v_mul_f32_e32 v98, 0x37800000, v97
	v_cndmask_b32_e32 v97, v97, v98, vcc
	v_cmp_class_f32_e32 vcc, v96, v250
	s_nop 1
	v_cndmask_b32_e32 v130, v97, v96, vcc
	global_load_dwordx4 v[96:99], v108, s[40:41] offset:400
	global_load_dwordx4 v[100:103], v108, s[40:41] offset:384
	global_load_dwordx4 v[104:107], v108, s[40:41] offset:464
	s_nop 0
	global_load_dwordx4 v[108:111], v108, s[40:41] offset:448
	v_div_scale_f32 v131, s[6:7], v130, v130, s9
	v_rcp_f32_e32 v132, v131
	s_cselect_b32 s6, 0, 0
	s_waitcnt lgkmcnt(0)
	s_barrier
; __device__ __forceinline__ unsigned cvtpk(float lo, float hi) { f32x2_t v = {lo, hi}; bf16x2_t b = __builtin_convertvector(v, bf16x2_t); return __builtin_bit_cast(unsigned, b); }
; __device__ __forceinline__ float bf2f(unsigned short h) { return __uint_as_float(((unsigned)h) << 16); }
; __device__ __forceinline__ void mem_unit(const MemArgs& A, int unit, char* lds, int wv) {
;     ...
;       const float rn = QSCALE_M / sqrtf(ss * (1.0f / 128.0f) + EPS);
; #pragma unroll
;       for (int d0 = 0; d0 < 8; ++d0) { const f32x4 g0 = *(const f32x4*)(A.gmq + d0 * 16 + hi * 8), g1 = *(const f32x4*)(A.gmq + d0 * 16 + hi * 8 + 4);
;           u32x4 w; w.x = cvtpk(bf2f((unsigned short)raw[d0][0]) * rn * g0.x, bf2f((unsigned short)raw[d0][1]) * rn * g0.y); w.y = cvtpk(bf2f((unsigned short)raw[d0][2]) * rn * g0.z, bf2f((unsigned short)raw[d0][3]) * rn * g0.w);
;           w.z = cvtpk(bf2f((unsigned short)raw[d0][4]) * rn * g1.x, bf2f((unsigned short)raw[d0][5]) * rn * g1.y); w.w = cvtpk(bf2f((unsigned short)raw[d0][6]) * rn * g1.z, bf2f((unsigned short)raw[d0][7]) * rn * g1.w);
;           qr[d0] = *reinterpret_cast<bf16x8*>(&w); } }
	v_fma_f32 v133, -v131, v132, 1.0
	v_fmac_f32_e32 v132, v133, v132
	v_div_scale_f32 v133, vcc, s9, v130, s9
	v_mul_f32_e32 v134, v133, v132
	v_fma_f32 v135, -v131, v134, v133
	v_fmac_f32_e32 v134, v135, v132
	v_fma_f32 v131, -v131, v134, v133
	v_div_fmas_f32 v131, v131, v132, v134
	v_div_fixup_f32 v148, v131, v130, s9
	v_pk_mul_f32 v[112:113], v[148:149], v[112:113] op_sel_hi:[0,1]
	s_waitcnt vmcnt(14)
	v_pk_mul_f32 v[28:29], v[28:29], v[112:113]
	s_nop 0
	v_cvt_pk_bf16_f32 v112, v28, v29
	v_pk_mul_f32 v[28:29], v[148:149], v[128:129] op_sel_hi:[0,1]
	v_pk_mul_f32 v[28:29], v[30:31], v[28:29]
	s_nop 0
	v_cvt_pk_bf16_f32 v113, v28, v29
	v_pk_mul_f32 v[28:29], v[148:149], v[114:115] op_sel_hi:[0,1]
	v_pk_mul_f32 v[24:25], v[24:25], v[28:29]
	s_nop 0
	v_cvt_pk_bf16_f32 v114, v24, v25
	v_pk_mul_f32 v[24:25], v[148:149], v[126:127] op_sel_hi:[0,1]
	v_pk_mul_f32 v[24:25], v[26:27], v[24:25]
	s_nop 0
	v_cvt_pk_bf16_f32 v115, v24, v25
	v_pk_mul_f32 v[24:25], v[148:149], v[116:117] op_sel_hi:[0,1]
	s_waitcnt vmcnt(12)
	v_pk_mul_f32 v[20:21], v[20:21], v[24:25]
	s_nop 0
	v_cvt_pk_bf16_f32 v116, v20, v21
	v_pk_mul_f32 v[20:21], v[148:149], v[124:125] op_sel_hi:[0,1]
	v_pk_mul_f32 v[20:21], v[22:23], v[20:21]
	s_nop 0
	v_cvt_pk_bf16_f32 v117, v20, v21
	v_pk_mul_f32 v[20:21], v[148:149], v[118:119] op_sel_hi:[0,1]
	v_pk_mul_f32 v[16:17], v[16:17], v[20:21]
	s_nop 0
	v_cvt_pk_bf16_f32 v118, v16, v17
	v_pk_mul_f32 v[16:17], v[148:149], v[122:123] op_sel_hi:[0,1]
	v_pk_mul_f32 v[16:17], v[18:19], v[16:17]
	s_nop 0
	v_cvt_pk_bf16_f32 v119, v16, v17
	v_pk_mul_f32 v[16:17], v[148:149], v[120:121] op_sel_hi:[0,1]
	s_waitcnt vmcnt(10)
	v_pk_mul_f32 v[12:13], v[12:13], v[16:17]
	v_mov_b32_e32 v16, 0
	v_cvt_pk_bf16_f32 v120, v12, v13
	v_pk_mul_f32 v[12:13], v[148:149], v[76:77] op_sel_hi:[0,1]
	v_pk_mul_f32 v[12:13], v[14:15], v[12:13]
	s_nop 0
	v_cvt_pk_bf16_f32 v121, v12, v13
	v_pk_mul_f32 v[12:13], v[148:149], v[74:75] op_sel_hi:[0,1]
	v_pk_mul_f32 v[8:9], v[8:9], v[12:13]
	v_or_b32_e32 v12, 0xe0, v176
	v_cvt_pk_bf16_f32 v122, v8, v9
	v_pk_mul_f32 v[8:9], v[148:149], v[72:73] op_sel_hi:[0,1]
	v_pk_mul_f32 v[8:9], v[10:11], v[8:9]
	v_or_b32_e32 v11, 0xc0, v176
	v_cvt_pk_bf16_f32 v123, v8, v9
	v_pk_mul_f32 v[8:9], v[148:149], v[70:71] op_sel_hi:[0,1]
	s_waitcnt vmcnt(8)
	v_pk_mul_f32 v[4:5], v[4:5], v[8:9]
	v_or_b32_e32 v10, 0xa0, v176
	v_cvt_pk_bf16_f32 v124, v4, v5
	v_pk_mul_f32 v[4:5], v[148:149], v[68:69] op_sel_hi:[0,1]
	v_pk_mul_f32 v[4:5], v[6:7], v[4:5]
	v_or_b32_e32 v9, 0x80, v176
	v_cvt_pk_bf16_f32 v125, v4, v5
	v_pk_mul_f32 v[4:5], v[148:149], v[66:67] op_sel_hi:[0,1]
	v_pk_mul_f32 v[0:1], v[4:5], v[0:1]
	v_lshlrev_b32_e32 v4, 1, v78
	v_cvt_pk_bf16_f32 v126, v0, v1
	v_pk_mul_f32 v[0:1], v[148:149], v[64:65] op_sel_hi:[0,1]
	v_pk_mul_f32 v[0:1], v[0:1], v[2:3]
	v_lshlrev_b32_e32 v2, 4, v78
	v_cvt_pk_bf16_f32 v127, v0, v1
	v_pk_mul_f32 v[0:1], v[148:149], v[62:63] op_sel_hi:[0,1]
	s_waitcnt vmcnt(6)
	v_pk_mul_f32 v[0:1], v[0:1], v[84:85]
	v_and_b32_e32 v3, 0xc0, v2
	v_cvt_pk_bf16_f32 v128, v0, v1
	v_pk_mul_f32 v[0:1], v[148:149], v[60:61] op_sel_hi:[0,1]
	v_pk_mul_f32 v[0:1], v[0:1], v[86:87]
	v_and_b32_e32 v4, 32, v4
	v_cvt_pk_bf16_f32 v129, v0, v1
	v_pk_mul_f32 v[0:1], v[148:149], v[58:59] op_sel_hi:[0,1]
	v_pk_mul_f32 v[0:1], v[0:1], v[80:81]
	v_lshlrev_b32_e32 v5, 8, v144
	v_cvt_pk_bf16_f32 v130, v0, v1
	v_pk_mul_f32 v[0:1], v[148:149], v[56:57] op_sel_hi:[0,1]
	v_pk_mul_f32 v[0:1], v[0:1], v[82:83]
	v_and_b32_e32 v2, 0xf0, v2
	v_cvt_pk_bf16_f32 v131, v0, v1
	v_pk_mul_f32 v[0:1], v[148:149], v[54:55] op_sel_hi:[0,1]
	s_waitcnt vmcnt(4)
	v_pk_mul_f32 v[0:1], v[0:1], v[92:93]
	v_or_b32_e32 v8, 0x60, v176
	v_cvt_pk_bf16_f32 v132, v0, v1
	v_pk_mul_f32 v[0:1], v[148:149], v[52:53] op_sel_hi:[0,1]
	v_pk_mul_f32 v[0:1], v[0:1], v[94:95]
	v_or_b32_e32 v7, 64, v176
	v_cvt_pk_bf16_f32 v133, v0, v1
	v_pk_mul_f32 v[0:1], v[148:149], v[50:51] op_sel_hi:[0,1]
	v_pk_mul_f32 v[0:1], v[0:1], v[88:89]
	v_or_b32_e32 v6, 32, v176
	v_cvt_pk_bf16_f32 v134, v0, v1
	v_pk_mul_f32 v[0:1], v[148:149], v[48:49] op_sel_hi:[0,1]
	v_pk_mul_f32 v[0:1], v[0:1], v[90:91]
	v_xor_b32_e32 v64, 0x80000000, v79
	v_cvt_pk_bf16_f32 v135, v0, v1
	v_pk_mul_f32 v[0:1], v[148:149], v[46:47] op_sel_hi:[0,1]
	s_waitcnt vmcnt(2)
; __device__ __forceinline__ unsigned cvtpk(float lo, float hi) { f32x2_t v = {lo, hi}; bf16x2_t b = __builtin_convertvector(v, bf16x2_t); return __builtin_bit_cast(unsigned, b); }
; __device__ __forceinline__ float bf2f(unsigned short h) { return __uint_as_float(((unsigned)h) << 16); }
; __device__ __forceinline__ int v_rd_base(int lane) { return ((lane & 3) << 3) | (((lane >> 2) & 3) << 6) | (((lane >> 4) & 1) << 5) | (((lane >> 5) & 1) << 8); }
; __device__ __forceinline__ void mem_unit(const MemArgs& A, int unit, char* lds, int wv) {
;     ...
;       for (int d0 = 0; d0 < 8; ++d0) { const f32x4 g0 = *(const f32x4*)(A.gmq + d0 * 16 + hi * 8), g1 = *(const f32x4*)(A.gmq + d0 * 16 + hi * 8 + 4);
;           u32x4 w; w.x = cvtpk(bf2f((unsigned short)raw[d0][0]) * rn * g0.x, bf2f((unsigned short)raw[d0][1]) * rn * g0.y); w.y = cvtpk(bf2f((unsigned short)raw[d0][2]) * rn * g0.z, bf2f((unsigned short)raw[d0][3]) * rn * g0.w);
;           w.z = cvtpk(bf2f((unsigned short)raw[d0][4]) * rn * g1.x, bf2f((unsigned short)raw[d0][5]) * rn * g1.y); w.w = cvtpk(bf2f((unsigned short)raw[d0][6]) * rn * g1.z, bf2f((unsigned short)raw[d0][7]) * rn * g1.w);
;           qr[d0] = *reinterpret_cast<bf16x8*>(&w); } }
;     __syncthreads();
;     float l_reg = 0; f32x16 o[4] = {};
;     const int vb0 = (int)(uintptr_t)V_lds + v_rd_base(lane);
; #pragma unroll 1
;     for (int t = 0; t < 4; ++t) {
;         f32x16 p0, p1; bf16x8 pa0, pa1, pa2, pa3;
; #pragma unroll
;         for (int r = 0; r < 16; ++r) { p0[r] = nM2; p1[r] = nM2; }
;         qkt<8>(p0, p1, K_lds + t * SHM_K, qr, r32, hi, 0);
	v_pk_mul_f32 v[0:1], v[0:1], v[100:101]
	v_mov_b32_e32 v65, v64
	v_cvt_pk_bf16_f32 v136, v0, v1
	v_pk_mul_f32 v[0:1], v[148:149], v[44:45] op_sel_hi:[0,1]
	v_pk_mul_f32 v[0:1], v[0:1], v[102:103]
	v_mov_b32_e32 v66, v64
	v_cvt_pk_bf16_f32 v137, v0, v1
	v_pk_mul_f32 v[0:1], v[148:149], v[42:43] op_sel_hi:[0,1]
	v_pk_mul_f32 v[0:1], v[0:1], v[96:97]
	v_mov_b32_e32 v67, v64
	v_cvt_pk_bf16_f32 v138, v0, v1
	v_pk_mul_f32 v[0:1], v[148:149], v[40:41] op_sel_hi:[0,1]
	v_pk_mul_f32 v[0:1], v[0:1], v[98:99]
	v_mov_b32_e32 v68, v64
	v_cvt_pk_bf16_f32 v139, v0, v1
	v_pk_mul_f32 v[0:1], v[148:149], v[38:39] op_sel_hi:[0,1]
	s_waitcnt vmcnt(0)
	v_pk_mul_f32 v[0:1], v[0:1], v[108:109]
	v_mov_b32_e32 v69, v64
	v_cvt_pk_bf16_f32 v140, v0, v1
	v_pk_mul_f32 v[0:1], v[148:149], v[36:37] op_sel_hi:[0,1]
	v_pk_mul_f32 v[0:1], v[0:1], v[110:111]
	v_mov_b32_e32 v70, v64
	v_cvt_pk_bf16_f32 v141, v0, v1
	v_pk_mul_f32 v[0:1], v[148:149], v[34:35] op_sel_hi:[0,1]
	v_pk_mul_f32 v[0:1], v[0:1], v[104:105]
	v_mov_b32_e32 v71, v64
	v_cvt_pk_bf16_f32 v142, v0, v1
	v_pk_mul_f32 v[0:1], v[148:149], v[32:33] op_sel_hi:[0,1]
	v_pk_mul_f32 v[0:1], v[0:1], v[106:107]
	v_mov_b32_e32 v148, 0
	v_cvt_pk_bf16_f32 v143, v0, v1
	v_lshlrev_b32_e32 v0, 3, v145
	v_and_b32_e32 v1, 24, v0
	v_and_b32_e32 v0, 0x100, v0
	v_add3_u32 v0, v0, s6, v3
	v_add3_u32 v147, v0, v4, v1
	v_bitop3_b32 v0, v12, v5, v2 bitop3:0xde
	v_add_u32_e32 v149, 0, v0
	v_bitop3_b32 v0, v11, v5, v2 bitop3:0xde
	v_add_u32_e32 v150, 0, v0
	v_bitop3_b32 v0, v10, v5, v2 bitop3:0xde
	v_add_u32_e32 v151, 0, v0
	v_bitop3_b32 v0, v9, v5, v2 bitop3:0xde
	v_add_u32_e32 v152, 0, v0
	v_bitop3_b32 v0, v8, v5, v2 bitop3:0xde
	v_add_u32_e32 v153, 0, v0
	v_bitop3_b32 v0, v7, v5, v2 bitop3:0xde
	v_add_u32_e32 v154, 0, v0
	v_bitop3_b32 v0, v6, v5, v2 bitop3:0xde
	v_add_u32_e32 v155, 0, v0
	v_bitop3_b32 v0, v176, v5, v2 bitop3:0xde
	v_mov_b32_e32 v72, v64
	v_mov_b32_e32 v73, v64
	v_mov_b32_e32 v74, v64
	v_mov_b32_e32 v75, v64
	v_mov_b32_e32 v76, v64
	v_mov_b32_e32 v77, v64
	v_mov_b32_e32 v78, v64
	v_mov_b32_e32 v79, v64
	v_add_u32_e32 v156, 0, v0
	v_mov_b32_e32 v0, 0
	v_mov_b32_e32 v1, v148
	v_mov_b32_e32 v2, v148
	v_mov_b32_e32 v3, v148
	v_mov_b32_e32 v4, v148
	v_mov_b32_e32 v5, v148
	v_mov_b32_e32 v6, v148
	v_mov_b32_e32 v7, v148
	v_mov_b32_e32 v8, v148
	v_mov_b32_e32 v9, v148
	v_mov_b32_e32 v10, v148
	v_mov_b32_e32 v11, v148
	v_mov_b32_e32 v12, v148
	v_mov_b32_e32 v13, v148
	v_mov_b32_e32 v14, v148
	v_mov_b32_e32 v15, v148
	v_mov_b32_e32 v17, v148
	v_mov_b32_e32 v18, v148
	v_mov_b32_e32 v19, v148
	v_mov_b32_e32 v20, v148
	v_mov_b32_e32 v21, v148
	v_mov_b32_e32 v22, v148
	v_mov_b32_e32 v23, v148
	v_mov_b32_e32 v24, v148
	v_mov_b32_e32 v25, v148
	v_mov_b32_e32 v26, v148
	v_mov_b32_e32 v27, v148
	v_mov_b32_e32 v28, v148
	v_mov_b32_e32 v29, v148
	v_mov_b32_e32 v30, v148
	v_mov_b32_e32 v31, v148
	v_mov_b32_e32 v32, 0
	v_mov_b32_e32 v33, v148
	v_mov_b32_e32 v34, v148
	v_mov_b32_e32 v35, v148
	v_mov_b32_e32 v36, v148
	v_mov_b32_e32 v37, v148
	v_mov_b32_e32 v38, v148
	v_mov_b32_e32 v39, v148
	v_mov_b32_e32 v40, v148
	v_mov_b32_e32 v41, v148
	v_mov_b32_e32 v42, v148
	v_mov_b32_e32 v43, v148
	v_mov_b32_e32 v44, v148
	v_mov_b32_e32 v45, v148
	v_mov_b32_e32 v46, v148
	v_mov_b32_e32 v47, v148
	v_mov_b32_e32 v48, 0
	v_mov_b32_e32 v49, v148
	v_mov_b32_e32 v50, v148
	v_mov_b32_e32 v51, v148
	v_mov_b32_e32 v52, v148
	v_mov_b32_e32 v53, v148
	v_mov_b32_e32 v54, v148
	v_mov_b32_e32 v55, v148
	v_mov_b32_e32 v56, v148
	v_mov_b32_e32 v57, v148
	v_mov_b32_e32 v58, v148
	v_mov_b32_e32 v59, v148
	v_mov_b32_e32 v60, v148
	v_mov_b32_e32 v61, v148
	v_mov_b32_e32 v62, v148
	v_mov_b32_e32 v63, v148
